# prep: modulation GEMV loads batched 16 per trip, silu staging with 34 loads in flight, hyena filter output layer unrolled x4 with its 16 weight loads issued together (both layers)
# speedup vs baseline: 1.0106x; 1.0106x over previous
; __device__ __forceinline__ float siluf(float v) { return v * __builtin_amdgcn_rcpf(1.f + __expf(-v)); }
; __device__ NOINL void prep_mod(const LAS Params* lp, LAS unsigned char* lds) {
;     ...
;         if (!have) { for (int i = tid; i < 17 * 1024; i += 512) { const float v = i < 16 * 1024 ? p.c[i] : p.c_ctx[i - 16 * 1024]; sc[i] = siluf(v); } have = true; __syncthreads(); }
.LBB0_9:
	s_and_b64 vcc, exec, s[18:19]
	s_barrier
	s_cbranch_vccnz .LBB0_14
	s_and_saveexec_b64 s[18:19], s[6:7]
	s_cbranch_execz .LBB0_13
	v_mov_b64_e32 v[2:3], v[16:17]
	global_load_dword v80, v[2:3], off
	v_lshl_add_u64 v[2:3], v[2:3], 0, s[14:15]
	global_load_dword v81, v[2:3], off
	v_lshl_add_u64 v[2:3], v[2:3], 0, s[14:15]
	global_load_dword v82, v[2:3], off
	v_lshl_add_u64 v[2:3], v[2:3], 0, s[14:15]
	global_load_dword v83, v[2:3], off
	v_lshl_add_u64 v[2:3], v[2:3], 0, s[14:15]
	global_load_dword v84, v[2:3], off
	v_lshl_add_u64 v[2:3], v[2:3], 0, s[14:15]
	global_load_dword v85, v[2:3], off
	v_lshl_add_u64 v[2:3], v[2:3], 0, s[14:15]
	global_load_dword v86, v[2:3], off
	v_lshl_add_u64 v[2:3], v[2:3], 0, s[14:15]
	global_load_dword v87, v[2:3], off
	v_lshl_add_u64 v[2:3], v[2:3], 0, s[14:15]
	global_load_dword v88, v[2:3], off
	v_lshl_add_u64 v[2:3], v[2:3], 0, s[14:15]
	global_load_dword v89, v[2:3], off
	v_lshl_add_u64 v[2:3], v[2:3], 0, s[14:15]
	global_load_dword v90, v[2:3], off
	v_lshl_add_u64 v[2:3], v[2:3], 0, s[14:15]
	global_load_dword v91, v[2:3], off
	v_lshl_add_u64 v[2:3], v[2:3], 0, s[14:15]
	global_load_dword v92, v[2:3], off
	v_lshl_add_u64 v[2:3], v[2:3], 0, s[14:15]
	global_load_dword v93, v[2:3], off
	v_lshl_add_u64 v[2:3], v[2:3], 0, s[14:15]
	global_load_dword v94, v[2:3], off
	v_lshl_add_u64 v[2:3], v[2:3], 0, s[14:15]
	global_load_dword v95, v[2:3], off
	v_lshl_add_u64 v[2:3], v[2:3], 0, s[14:15]
	global_load_dword v96, v[2:3], off
	v_lshl_add_u64 v[2:3], v[2:3], 0, s[14:15]
	global_load_dword v97, v[2:3], off
	v_lshl_add_u64 v[2:3], v[2:3], 0, s[14:15]
	global_load_dword v98, v[2:3], off
	v_lshl_add_u64 v[2:3], v[2:3], 0, s[14:15]
	global_load_dword v99, v[2:3], off
	v_lshl_add_u64 v[2:3], v[2:3], 0, s[14:15]
	global_load_dword v100, v[2:3], off
	v_lshl_add_u64 v[2:3], v[2:3], 0, s[14:15]
	global_load_dword v101, v[2:3], off
	v_lshl_add_u64 v[2:3], v[2:3], 0, s[14:15]
	global_load_dword v102, v[2:3], off
	v_lshl_add_u64 v[2:3], v[2:3], 0, s[14:15]
	global_load_dword v103, v[2:3], off
	v_lshl_add_u64 v[2:3], v[2:3], 0, s[14:15]
	global_load_dword v104, v[2:3], off
	v_lshl_add_u64 v[2:3], v[2:3], 0, s[14:15]
	global_load_dword v105, v[2:3], off
	v_lshl_add_u64 v[2:3], v[2:3], 0, s[14:15]
	global_load_dword v106, v[2:3], off
	v_lshl_add_u64 v[2:3], v[2:3], 0, s[14:15]
	global_load_dword v107, v[2:3], off
	v_lshl_add_u64 v[2:3], v[2:3], 0, s[14:15]
	global_load_dword v108, v[2:3], off
	v_lshl_add_u64 v[2:3], v[2:3], 0, s[14:15]
	global_load_dword v109, v[2:3], off
	v_lshl_add_u64 v[2:3], v[2:3], 0, s[14:15]
	global_load_dword v110, v[2:3], off
	v_lshl_add_u64 v[2:3], v[2:3], 0, s[14:15]
	global_load_dword v111, v[2:3], off
	v_lshl_add_u64 v[2:3], v[2:3], 0, s[14:15]
	v_mov_b32_e32 v115, 0
	v_add_u32_e32 v114, 0x4000, v10
	v_lshl_add_u64 v[6:7], v[114:115], 2, s[0:1]
	v_lshl_add_u64 v[6:7], v[6:7], 0, s[12:13]
	global_load_dword v112, v[6:7], off
	v_add_u32_e32 v114, 0x4200, v10
	v_lshl_add_u64 v[6:7], v[114:115], 2, s[0:1]
	v_lshl_add_u64 v[6:7], v[6:7], 0, s[12:13]
	global_load_dword v113, v[6:7], off
	v_add_u32_e32 v4, 0x10000, v51
	s_waitcnt vmcnt(33)
	v_mul_f32_e32 v116, 0xbfb8aa3b, v80
	v_exp_f32_e32 v116, v116
	s_nop 0
	v_add_f32_e32 v116, 1.0, v116
	v_rcp_f32_e32 v116, v116
	s_nop 0
	v_mul_f32_e32 v80, v80, v116
	ds_write_b32 v51, v80
	s_waitcnt vmcnt(32)
	v_mul_f32_e32 v117, 0xbfb8aa3b, v81
	v_exp_f32_e32 v117, v117
	s_nop 0
	v_add_f32_e32 v117, 1.0, v117
	v_rcp_f32_e32 v117, v117
	s_nop 0
	v_mul_f32_e32 v81, v81, v117
	ds_write_b32 v51, v81 offset:2048
	s_waitcnt vmcnt(31)
	v_mul_f32_e32 v118, 0xbfb8aa3b, v82
	v_exp_f32_e32 v118, v118
	s_nop 0
	v_add_f32_e32 v118, 1.0, v118
	v_rcp_f32_e32 v118, v118
	s_nop 0
	v_mul_f32_e32 v82, v82, v118
	ds_write_b32 v51, v82 offset:4096
	s_waitcnt vmcnt(30)
	v_mul_f32_e32 v119, 0xbfb8aa3b, v83
	v_exp_f32_e32 v119, v119
	s_nop 0
	v_add_f32_e32 v119, 1.0, v119
	v_rcp_f32_e32 v119, v119
	s_nop 0
	v_mul_f32_e32 v83, v83, v119
	ds_write_b32 v51, v83 offset:6144
	s_waitcnt vmcnt(29)
	v_mul_f32_e32 v116, 0xbfb8aa3b, v84
	v_exp_f32_e32 v116, v116
	s_nop 0
	v_add_f32_e32 v116, 1.0, v116
	v_rcp_f32_e32 v116, v116
	s_nop 0
	v_mul_f32_e32 v84, v84, v116
	ds_write_b32 v51, v84 offset:8192
	s_waitcnt vmcnt(28)
	v_mul_f32_e32 v117, 0xbfb8aa3b, v85
	v_exp_f32_e32 v117, v117
	s_nop 0
	v_add_f32_e32 v117, 1.0, v117
	v_rcp_f32_e32 v117, v117
	s_nop 0
	v_mul_f32_e32 v85, v85, v117
	ds_write_b32 v51, v85 offset:10240
	s_waitcnt vmcnt(27)
	v_mul_f32_e32 v118, 0xbfb8aa3b, v86
	v_exp_f32_e32 v118, v118
	s_nop 0
	v_add_f32_e32 v118, 1.0, v118
	v_rcp_f32_e32 v118, v118
	s_nop 0
	v_mul_f32_e32 v86, v86, v118
	ds_write_b32 v51, v86 offset:12288
	s_waitcnt vmcnt(26)
	v_mul_f32_e32 v119, 0xbfb8aa3b, v87
	v_exp_f32_e32 v119, v119
	s_nop 0
	v_add_f32_e32 v119, 1.0, v119
	v_rcp_f32_e32 v119, v119
	s_nop 0
	v_mul_f32_e32 v87, v87, v119
	ds_write_b32 v51, v87 offset:14336
	s_waitcnt vmcnt(25)
	v_mul_f32_e32 v116, 0xbfb8aa3b, v88
	v_exp_f32_e32 v116, v116
	s_nop 0
	v_add_f32_e32 v116, 1.0, v116
	v_rcp_f32_e32 v116, v116
	s_nop 0
	v_mul_f32_e32 v88, v88, v116
	ds_write_b32 v51, v88 offset:16384
	s_waitcnt vmcnt(24)
	v_mul_f32_e32 v117, 0xbfb8aa3b, v89
	v_exp_f32_e32 v117, v117
	s_nop 0
	v_add_f32_e32 v117, 1.0, v117
	v_rcp_f32_e32 v117, v117
	s_nop 0
	v_mul_f32_e32 v89, v89, v117
	ds_write_b32 v51, v89 offset:18432
	s_waitcnt vmcnt(23)
; __device__ __forceinline__ float siluf(float v) { return v * __builtin_amdgcn_rcpf(1.f + __expf(-v)); }
; __device__ NOINL void prep_mod(const LAS Params* lp, LAS unsigned char* lds) {
;     ...
;         if (!have) { for (int i = tid; i < 17 * 1024; i += 512) { const float v = i < 16 * 1024 ? p.c[i] : p.c_ctx[i - 16 * 1024]; sc[i] = siluf(v); } have = true; __syncthreads(); }
	v_mul_f32_e32 v118, 0xbfb8aa3b, v90
	v_exp_f32_e32 v118, v118
	s_nop 0
	v_add_f32_e32 v118, 1.0, v118
	v_rcp_f32_e32 v118, v118
	s_nop 0
	v_mul_f32_e32 v90, v90, v118
	ds_write_b32 v51, v90 offset:20480
	s_waitcnt vmcnt(22)
	v_mul_f32_e32 v119, 0xbfb8aa3b, v91
	v_exp_f32_e32 v119, v119
	s_nop 0
	v_add_f32_e32 v119, 1.0, v119
	v_rcp_f32_e32 v119, v119
	s_nop 0
	v_mul_f32_e32 v91, v91, v119
	ds_write_b32 v51, v91 offset:22528
	s_waitcnt vmcnt(21)
	v_mul_f32_e32 v116, 0xbfb8aa3b, v92
	v_exp_f32_e32 v116, v116
	s_nop 0
	v_add_f32_e32 v116, 1.0, v116
	v_rcp_f32_e32 v116, v116
	s_nop 0
	v_mul_f32_e32 v92, v92, v116
	ds_write_b32 v51, v92 offset:24576
	s_waitcnt vmcnt(20)
	v_mul_f32_e32 v117, 0xbfb8aa3b, v93
	v_exp_f32_e32 v117, v117
	s_nop 0
	v_add_f32_e32 v117, 1.0, v117
	v_rcp_f32_e32 v117, v117
	s_nop 0
	v_mul_f32_e32 v93, v93, v117
	ds_write_b32 v51, v93 offset:26624
	s_waitcnt vmcnt(19)
	v_mul_f32_e32 v118, 0xbfb8aa3b, v94
	v_exp_f32_e32 v118, v118
	s_nop 0
	v_add_f32_e32 v118, 1.0, v118
	v_rcp_f32_e32 v118, v118
	s_nop 0
	v_mul_f32_e32 v94, v94, v118
	ds_write_b32 v51, v94 offset:28672
	s_waitcnt vmcnt(18)
	v_mul_f32_e32 v119, 0xbfb8aa3b, v95
	v_exp_f32_e32 v119, v119
	s_nop 0
	v_add_f32_e32 v119, 1.0, v119
	v_rcp_f32_e32 v119, v119
	s_nop 0
	v_mul_f32_e32 v95, v95, v119
	ds_write_b32 v51, v95 offset:30720
	s_waitcnt vmcnt(17)
	v_mul_f32_e32 v116, 0xbfb8aa3b, v96
	v_exp_f32_e32 v116, v116
	s_nop 0
	v_add_f32_e32 v116, 1.0, v116
	v_rcp_f32_e32 v116, v116
	s_nop 0
	v_mul_f32_e32 v96, v96, v116
	ds_write_b32 v51, v96 offset:32768
	s_waitcnt vmcnt(16)
	v_mul_f32_e32 v117, 0xbfb8aa3b, v97
	v_exp_f32_e32 v117, v117
	s_nop 0
	v_add_f32_e32 v117, 1.0, v117
	v_rcp_f32_e32 v117, v117
	s_nop 0
	v_mul_f32_e32 v97, v97, v117
	ds_write_b32 v51, v97 offset:34816
	s_waitcnt vmcnt(15)
	v_mul_f32_e32 v118, 0xbfb8aa3b, v98
	v_exp_f32_e32 v118, v118
	s_nop 0
	v_add_f32_e32 v118, 1.0, v118
	v_rcp_f32_e32 v118, v118
	s_nop 0
	v_mul_f32_e32 v98, v98, v118
	ds_write_b32 v51, v98 offset:36864
	s_waitcnt vmcnt(14)
	v_mul_f32_e32 v119, 0xbfb8aa3b, v99
	v_exp_f32_e32 v119, v119
	s_nop 0
	v_add_f32_e32 v119, 1.0, v119
	v_rcp_f32_e32 v119, v119
	s_nop 0
	v_mul_f32_e32 v99, v99, v119
	ds_write_b32 v51, v99 offset:38912
	s_waitcnt vmcnt(13)
	v_mul_f32_e32 v116, 0xbfb8aa3b, v100
	v_exp_f32_e32 v116, v116
	s_nop 0
	v_add_f32_e32 v116, 1.0, v116
	v_rcp_f32_e32 v116, v116
	s_nop 0
	v_mul_f32_e32 v100, v100, v116
	ds_write_b32 v51, v100 offset:40960
	s_waitcnt vmcnt(12)
	v_mul_f32_e32 v117, 0xbfb8aa3b, v101
	v_exp_f32_e32 v117, v117
	s_nop 0
	v_add_f32_e32 v117, 1.0, v117
	v_rcp_f32_e32 v117, v117
	s_nop 0
	v_mul_f32_e32 v101, v101, v117
	ds_write_b32 v51, v101 offset:43008
	s_waitcnt vmcnt(11)
	v_mul_f32_e32 v118, 0xbfb8aa3b, v102
	v_exp_f32_e32 v118, v118
	s_nop 0
	v_add_f32_e32 v118, 1.0, v118
	v_rcp_f32_e32 v118, v118
	s_nop 0
	v_mul_f32_e32 v102, v102, v118
	ds_write_b32 v51, v102 offset:45056
	s_waitcnt vmcnt(10)
	v_mul_f32_e32 v119, 0xbfb8aa3b, v103
	v_exp_f32_e32 v119, v119
	s_nop 0
	v_add_f32_e32 v119, 1.0, v119
	v_rcp_f32_e32 v119, v119
	s_nop 0
	v_mul_f32_e32 v103, v103, v119
	ds_write_b32 v51, v103 offset:47104
	s_waitcnt vmcnt(9)
	v_mul_f32_e32 v116, 0xbfb8aa3b, v104
	v_exp_f32_e32 v116, v116
	s_nop 0
	v_add_f32_e32 v116, 1.0, v116
	v_rcp_f32_e32 v116, v116
	s_nop 0
	v_mul_f32_e32 v104, v104, v116
	ds_write_b32 v51, v104 offset:49152
	s_waitcnt vmcnt(8)
	v_mul_f32_e32 v117, 0xbfb8aa3b, v105
	v_exp_f32_e32 v117, v117
	s_nop 0
	v_add_f32_e32 v117, 1.0, v117
	v_rcp_f32_e32 v117, v117
	s_nop 0
	v_mul_f32_e32 v105, v105, v117
	ds_write_b32 v51, v105 offset:51200
	s_waitcnt vmcnt(7)
	v_mul_f32_e32 v118, 0xbfb8aa3b, v106
	v_exp_f32_e32 v118, v118
	s_nop 0
	v_add_f32_e32 v118, 1.0, v118
	v_rcp_f32_e32 v118, v118
	s_nop 0
	v_mul_f32_e32 v106, v106, v118
	ds_write_b32 v51, v106 offset:53248
	s_waitcnt vmcnt(6)
	v_mul_f32_e32 v119, 0xbfb8aa3b, v107
	v_exp_f32_e32 v119, v119
	s_nop 0
	v_add_f32_e32 v119, 1.0, v119
	v_rcp_f32_e32 v119, v119
	s_nop 0
	v_mul_f32_e32 v107, v107, v119
	ds_write_b32 v51, v107 offset:55296
	s_waitcnt vmcnt(5)
	v_mul_f32_e32 v116, 0xbfb8aa3b, v108
	v_exp_f32_e32 v116, v116
	s_nop 0
	v_add_f32_e32 v116, 1.0, v116
	v_rcp_f32_e32 v116, v116
	s_nop 0
	v_mul_f32_e32 v108, v108, v116
	ds_write_b32 v51, v108 offset:57344
	s_waitcnt vmcnt(4)
	v_mul_f32_e32 v117, 0xbfb8aa3b, v109
	v_exp_f32_e32 v117, v117
	s_nop 0
	v_add_f32_e32 v117, 1.0, v117
	v_rcp_f32_e32 v117, v117
	s_nop 0
	v_mul_f32_e32 v109, v109, v117
	ds_write_b32 v51, v109 offset:59392
	s_waitcnt vmcnt(3)
	v_mul_f32_e32 v118, 0xbfb8aa3b, v110
	v_exp_f32_e32 v118, v118
	s_nop 0
	v_add_f32_e32 v118, 1.0, v118
	v_rcp_f32_e32 v118, v118
	s_nop 0
	v_mul_f32_e32 v110, v110, v118
	ds_write_b32 v51, v110 offset:61440
	s_waitcnt vmcnt(2)
	v_mul_f32_e32 v119, 0xbfb8aa3b, v111
	v_exp_f32_e32 v119, v119
	s_nop 0
	v_add_f32_e32 v119, 1.0, v119
	v_rcp_f32_e32 v119, v119
	s_nop 0
	v_mul_f32_e32 v111, v111, v119
	ds_write_b32 v51, v111 offset:63488
	s_waitcnt vmcnt(1)
	v_mul_f32_e32 v116, 0xbfb8aa3b, v112
	v_exp_f32_e32 v116, v116
	s_nop 0
	v_add_f32_e32 v116, 1.0, v116
	v_rcp_f32_e32 v116, v116
	s_nop 0
	v_mul_f32_e32 v112, v112, v116
	ds_write_b32 v4, v112
	s_waitcnt vmcnt(0)
	v_mul_f32_e32 v117, 0xbfb8aa3b, v113
	v_exp_f32_e32 v117, v117
	s_nop 0
	v_add_f32_e32 v117, 1.0, v117
	v_rcp_f32_e32 v117, v117
	s_nop 0
	v_mul_f32_e32 v113, v113, v117
	ds_write_b32 v4, v113 offset:2048

; #define LAS __attribute__((address_space(3)))
; __device__ NOINL void prep_mod(const LAS Params* lp, LAS unsigned char* lds) {
;     ...
;         const float* wp = p.mod_w + (size_t)l * DM * 6144 + n0 + lane;
; #pragma unroll 4
;         for (int k = w * 128; k < w * 128 + 128; k += 4) {
;             const float w0 = wp[(size_t)k * 6144], w1 = wp[(size_t)(k + 1) * 6144], w2 = wp[(size_t)(k + 2) * 6144], w3 = wp[(size_t)(k + 3) * 6144];
; #pragma unroll
;             for (int r = 0; r < 17; ++r) { const f32x4 sv = *(const LAS f32x4*)(sc + r * 1024 + k); acc[r] += sv[0] * w0 + sv[1] * w1 + sv[2] * w2 + sv[3] * w3; }
.LBB0_15:
	v_add_co_u32_e32 v80, vcc, s26, v20
	s_nop 1
	v_addc_co_u32_e32 v81, vcc, -1, v21, vcc
	global_load_dword v82, v[80:81], off
	v_add_co_u32_e32 v80, vcc, s27, v20
	s_nop 1
	v_addc_co_u32_e32 v81, vcc, -1, v21, vcc
	global_load_dword v84, v[80:81], off
	v_add_co_u32_e32 v80, vcc, s28, v20
	s_nop 1
	v_addc_co_u32_e32 v81, vcc, -1, v21, vcc
	global_load_dword v86, v[80:81], off
	v_add_co_u32_e32 v80, vcc, s29, v20
	s_nop 1
	v_addc_co_u32_e32 v81, vcc, -1, v21, vcc
	global_load_dword v88, v[80:81], off
	v_add_co_u32_e32 v80, vcc, s30, v20
	s_nop 1
	v_addc_co_u32_e32 v81, vcc, -1, v21, vcc
	global_load_dword v90, v[80:81], off
	v_add_co_u32_e32 v80, vcc, s31, v20
	s_nop 1
	v_addc_co_u32_e32 v81, vcc, -1, v21, vcc
	global_load_dword v92, v[80:81], off
	v_add_co_u32_e32 v80, vcc, s34, v20
	s_nop 1
	v_addc_co_u32_e32 v81, vcc, -1, v21, vcc
	global_load_dword v94, v[80:81], off
	v_add_co_u32_e32 v80, vcc, s35, v20
	s_nop 1
	v_addc_co_u32_e32 v81, vcc, -1, v21, vcc
	global_load_dword v96, v[80:81], off
	v_add_co_u32_e32 v80, vcc, s36, v20
	s_nop 1
	v_addc_co_u32_e32 v81, vcc, -1, v21, vcc
	global_load_dword v98, v[80:81], off
	v_add_co_u32_e32 v80, vcc, s37, v20
	s_nop 1
	v_addc_co_u32_e32 v81, vcc, -1, v21, vcc
	global_load_dword v100, v[80:81], off
	v_add_co_u32_e32 v80, vcc, s38, v20
	s_nop 1
	v_addc_co_u32_e32 v81, vcc, -1, v21, vcc
	global_load_dword v102, v[80:81], off
	v_add_co_u32_e32 v80, vcc, s39, v20
	s_nop 1
	v_addc_co_u32_e32 v81, vcc, -1, v21, vcc
	global_load_dword v104, v[80:81], off
	v_add_co_u32_e32 v80, vcc, s40, v20
	s_nop 1
	v_addc_co_u32_e32 v81, vcc, -1, v21, vcc
	v_add_co_u32_e32 v106, vcc, s41, v20
	global_load_dword v108, v[80:81], off
	s_nop 0
	v_addc_co_u32_e32 v107, vcc, -1, v21, vcc
	global_load_dword v110, v[106:107], off
	v_add_co_u32_e32 v106, vcc, s42, v20
	s_nop 1
	v_addc_co_u32_e32 v107, vcc, -1, v21, vcc
	global_load_dword v112, v[106:107], off
	global_load_dword v114, v[20:21], off
	v_add_u32_e32 v55, 16, v55
	s_nop 0
	s_nop 1
	s_nop 1
	s_nop 1
	ds_read_b128 v[40:43], v54
	ds_read_b128 v[44:47], v54 offset:16
	ds_read_b128 v[6:9], v54 offset:32
	ds_read_b128 v[2:5], v54 offset:48
	ds_read_b128 v[56:59], v54 offset:4096
	s_waitcnt lgkmcnt(4)
	v_mov_b32_e32 v22, v40
	s_waitcnt lgkmcnt(0)
	v_mov_b32_e32 v23, v56
	v_mov_b32_e32 v56, v41
	s_waitcnt vmcnt(14)
	v_pk_mul_f32 v[40:41], v[84:85], v[56:57] op_sel_hi:[0,1]
	v_pk_fma_f32 v[22:23], v[82:83], v[22:23], v[40:41] op_sel_hi:[0,1,1]
	v_mov_b32_e32 v40, v42
	v_mov_b32_e32 v41, v58
	v_mov_b32_e32 v58, v43
	s_waitcnt vmcnt(13)
	v_pk_fma_f32 v[22:23], v[86:87], v[40:41], v[22:23] op_sel_hi:[0,1,1]
	s_waitcnt vmcnt(12)
	v_pk_fma_f32 v[22:23], v[88:89], v[58:59], v[22:23] op_sel_hi:[0,1,1]
	v_pk_add_f32 v[56:57], v[24:25], v[22:23]
	ds_read_b128 v[22:25], v54 offset:8192
	ds_read_b128 v[40:43], v54 offset:12288
	s_waitcnt lgkmcnt(1)
	v_mov_b32_e32 v58, v22
	s_waitcnt lgkmcnt(0)
	v_mov_b32_e32 v59, v40
	v_mov_b32_e32 v40, v23
	v_pk_mul_f32 v[22:23], v[84:85], v[40:41] op_sel_hi:[0,1]
	v_pk_fma_f32 v[22:23], v[82:83], v[58:59], v[22:23] op_sel_hi:[0,1,1]
	v_mov_b32_e32 v40, v24
	v_mov_b32_e32 v41, v42
	v_pk_fma_f32 v[22:23], v[86:87], v[40:41], v[22:23] op_sel_hi:[0,1,1]
	v_mov_b32_e32 v42, v25
	v_pk_fma_f32 v[22:23], v[88:89], v[42:43], v[22:23] op_sel_hi:[0,1,1]
	v_pk_add_f32 v[58:59], v[26:27], v[22:23]
	ds_read_b128 v[22:25], v54 offset:16384
	ds_read_b128 v[40:43], v54 offset:20480
	s_waitcnt lgkmcnt(1)
	v_mov_b32_e32 v26, v22
	s_waitcnt lgkmcnt(0)
	v_mov_b32_e32 v27, v40
	v_mov_b32_e32 v40, v23
	v_pk_mul_f32 v[22:23], v[84:85], v[40:41] op_sel_hi:[0,1]
	v_pk_fma_f32 v[22:23], v[82:83], v[26:27], v[22:23] op_sel_hi:[0,1,1]
	v_mov_b32_e32 v26, v24
	v_mov_b32_e32 v27, v42
	v_pk_fma_f32 v[22:23], v[86:87], v[26:27], v[22:23] op_sel_hi:[0,1,1]
	v_mov_b32_e32 v42, v25
	v_pk_fma_f32 v[22:23], v[88:89], v[42:43], v[22:23] op_sel_hi:[0,1,1]
	v_pk_add_f32 v[66:67], v[28:29], v[22:23]
	ds_read_b128 v[22:25], v54 offset:24576
	ds_read_b128 v[26:29], v54 offset:28672
	s_waitcnt lgkmcnt(1)
	v_mov_b32_e32 v40, v22
	s_waitcnt lgkmcnt(0)
	v_mov_b32_e32 v41, v26
	v_mov_b32_e32 v26, v23
	v_pk_mul_f32 v[22:23], v[84:85], v[26:27] op_sel_hi:[0,1]
	v_pk_fma_f32 v[22:23], v[82:83], v[40:41], v[22:23] op_sel_hi:[0,1,1]
	v_mov_b32_e32 v26, v24
	v_mov_b32_e32 v27, v28
	v_pk_fma_f32 v[22:23], v[86:87], v[26:27], v[22:23] op_sel_hi:[0,1,1]
	v_mov_b32_e32 v28, v25
	v_pk_fma_f32 v[22:23], v[88:89], v[28:29], v[22:23] op_sel_hi:[0,1,1]
	v_pk_add_f32 v[68:69], v[30:31], v[22:23]
	ds_read_b128 v[22:25], v54 offset:32768
	ds_read_b128 v[26:29], v54 offset:36864
	s_waitcnt lgkmcnt(1)
	v_mov_b32_e32 v30, v22
	s_waitcnt lgkmcnt(0)
	v_mov_b32_e32 v31, v26
	v_mov_b32_e32 v26, v23
	v_pk_mul_f32 v[22:23], v[84:85], v[26:27] op_sel_hi:[0,1]
	v_pk_fma_f32 v[22:23], v[82:83], v[30:31], v[22:23] op_sel_hi:[0,1,1]
	v_mov_b32_e32 v26, v24
	v_mov_b32_e32 v27, v28
	v_pk_fma_f32 v[22:23], v[86:87], v[26:27], v[22:23] op_sel_hi:[0,1,1]
	v_mov_b32_e32 v28, v25
	v_pk_fma_f32 v[22:23], v[88:89], v[28:29], v[22:23] op_sel_hi:[0,1,1]
	v_pk_add_f32 v[70:71], v[32:33], v[22:23]
	ds_read_b128 v[22:25], v54 offset:40960
	ds_read_b128 v[26:29], v54 offset:45056
	s_waitcnt lgkmcnt(1)
	v_mov_b32_e32 v30, v22
	s_waitcnt lgkmcnt(0)
	v_mov_b32_e32 v31, v26
	v_mov_b32_e32 v26, v23
	v_pk_mul_f32 v[22:23], v[84:85], v[26:27] op_sel_hi:[0,1]
	v_pk_fma_f32 v[22:23], v[82:83], v[30:31], v[22:23] op_sel_hi:[0,1,1]
	v_mov_b32_e32 v26, v24
	v_mov_b32_e32 v27, v28
	v_pk_fma_f32 v[22:23], v[86:87], v[26:27], v[22:23] op_sel_hi:[0,1,1]
	v_mov_b32_e32 v28, v25
	v_pk_fma_f32 v[22:23], v[88:89], v[28:29], v[22:23] op_sel_hi:[0,1,1]
	v_pk_add_f32 v[72:73], v[34:35], v[22:23]
	ds_read_b128 v[22:25], v54 offset:49152
	ds_read_b128 v[26:29], v54 offset:53248
	s_waitcnt lgkmcnt(1)
; #define LAS __attribute__((address_space(3)))
; __device__ NOINL void prep_mod(const LAS Params* lp, LAS unsigned char* lds) {
;     ...
;         for (int k = w * 128; k < w * 128 + 128; k += 4) {
;             const float w0 = wp[(size_t)k * 6144], w1 = wp[(size_t)(k + 1) * 6144], w2 = wp[(size_t)(k + 2) * 6144], w3 = wp[(size_t)(k + 3) * 6144];
; #pragma unroll
;             for (int r = 0; r < 17; ++r) { const f32x4 sv = *(const LAS f32x4*)(sc + r * 1024 + k); acc[r] += sv[0] * w0 + sv[1] * w1 + sv[2] * w2 + sv[3] * w3; }
	v_mov_b32_e32 v30, v22
	s_waitcnt lgkmcnt(0)
	v_mov_b32_e32 v31, v26
	v_mov_b32_e32 v26, v23
	v_pk_mul_f32 v[22:23], v[84:85], v[26:27] op_sel_hi:[0,1]
	v_pk_fma_f32 v[22:23], v[82:83], v[30:31], v[22:23] op_sel_hi:[0,1,1]
	v_mov_b32_e32 v26, v24
	v_mov_b32_e32 v27, v28
	v_pk_fma_f32 v[22:23], v[86:87], v[26:27], v[22:23] op_sel_hi:[0,1,1]
	v_mov_b32_e32 v28, v25
	v_pk_fma_f32 v[22:23], v[88:89], v[28:29], v[22:23] op_sel_hi:[0,1,1]
	v_pk_add_f32 v[34:35], v[36:37], v[22:23]
	ds_read_b128 v[22:25], v54 offset:57344
	ds_read_b128 v[26:29], v54 offset:61440
	s_waitcnt lgkmcnt(1)
	v_mov_b32_e32 v30, v22
	s_waitcnt lgkmcnt(0)
	v_mov_b32_e32 v31, v26
	v_mov_b32_e32 v26, v23
	v_pk_mul_f32 v[22:23], v[84:85], v[26:27] op_sel_hi:[0,1]
	v_pk_fma_f32 v[22:23], v[82:83], v[30:31], v[22:23] op_sel_hi:[0,1,1]
	v_mov_b32_e32 v26, v24
	v_mov_b32_e32 v27, v28
	v_pk_fma_f32 v[22:23], v[86:87], v[26:27], v[22:23] op_sel_hi:[0,1,1]
	v_mov_b32_e32 v28, v25
	v_pk_fma_f32 v[22:23], v[88:89], v[28:29], v[22:23] op_sel_hi:[0,1,1]
	v_pk_add_f32 v[36:37], v[38:39], v[22:23]
	v_add_u32_e32 v22, 0x10000, v54
	ds_read_b128 v[22:25], v22
	v_mov_b32_e32 v83, v84
	v_mov_b32_e32 v87, v88
	v_mov_b32_e32 v26, v44
	s_waitcnt lgkmcnt(0)
	v_pk_mul_f32 v[22:23], v[82:83], v[22:23]
	v_pk_mul_f32 v[24:25], v[86:87], v[24:25]
	v_add_f32_e32 v22, v22, v23
	v_add_f32_e32 v22, v24, v22
	v_add_f32_e32 v22, v25, v22
	v_add_f32_e32 v43, v12, v22
	s_nop 1
	s_nop 1
	s_nop 1
	s_nop 1
	ds_read_b128 v[22:25], v54 offset:4112
	s_waitcnt lgkmcnt(0)
	v_mov_b32_e32 v27, v22
	v_mov_b32_e32 v22, v45
	s_waitcnt vmcnt(10)
	v_pk_mul_f32 v[22:23], v[92:93], v[22:23] op_sel_hi:[0,1]
	v_pk_fma_f32 v[22:23], v[90:91], v[26:27], v[22:23] op_sel_hi:[0,1,1]
	v_mov_b32_e32 v26, v46
	v_mov_b32_e32 v27, v24
	v_mov_b32_e32 v24, v47
	s_waitcnt vmcnt(9)
	v_pk_fma_f32 v[22:23], v[94:95], v[26:27], v[22:23] op_sel_hi:[0,1,1]
	ds_read_b128 v[26:29], v54 offset:8208
	ds_read_b128 v[30:33], v54 offset:12304
	s_waitcnt vmcnt(8)
	v_pk_fma_f32 v[22:23], v[96:97], v[24:25], v[22:23] op_sel_hi:[0,1,1]
	v_pk_add_f32 v[24:25], v[56:57], v[22:23]
	s_waitcnt lgkmcnt(0)
	v_mov_b32_e32 v23, v30
	v_mov_b32_e32 v30, v27
	v_mov_b32_e32 v22, v26
	v_pk_mul_f32 v[26:27], v[92:93], v[30:31] op_sel_hi:[0,1]
	v_pk_fma_f32 v[22:23], v[90:91], v[22:23], v[26:27] op_sel_hi:[0,1,1]
	v_mov_b32_e32 v26, v28
	v_mov_b32_e32 v27, v32
	v_mov_b32_e32 v32, v29
	ds_read_b128 v[28:31], v54 offset:16400
	ds_read_b128 v[44:47], v54 offset:20496
	v_pk_fma_f32 v[22:23], v[94:95], v[26:27], v[22:23] op_sel_hi:[0,1,1]
	v_pk_fma_f32 v[22:23], v[96:97], v[32:33], v[22:23] op_sel_hi:[0,1,1]
	v_pk_add_f32 v[26:27], v[58:59], v[22:23]
	s_waitcnt lgkmcnt(1)
	v_mov_b32_e32 v22, v28
	s_waitcnt lgkmcnt(0)
	v_mov_b32_e32 v23, v44
	v_mov_b32_e32 v44, v29
	v_pk_mul_f32 v[28:29], v[92:93], v[44:45] op_sel_hi:[0,1]
	v_pk_fma_f32 v[22:23], v[90:91], v[22:23], v[28:29] op_sel_hi:[0,1,1]
	v_mov_b32_e32 v28, v30
	v_mov_b32_e32 v29, v46
	v_pk_fma_f32 v[22:23], v[94:95], v[28:29], v[22:23] op_sel_hi:[0,1,1]
	v_mov_b32_e32 v46, v31
	v_pk_fma_f32 v[22:23], v[96:97], v[46:47], v[22:23] op_sel_hi:[0,1,1]
	ds_read_b128 v[30:33], v54 offset:24592
	ds_read_b128 v[44:47], v54 offset:28688
	v_pk_add_f32 v[28:29], v[66:67], v[22:23]
	s_waitcnt lgkmcnt(1)
	v_mov_b32_e32 v22, v30
	s_waitcnt lgkmcnt(0)
	v_mov_b32_e32 v23, v44
	v_mov_b32_e32 v44, v31
	v_pk_mul_f32 v[30:31], v[92:93], v[44:45] op_sel_hi:[0,1]
	v_pk_fma_f32 v[22:23], v[90:91], v[22:23], v[30:31] op_sel_hi:[0,1,1]
	v_mov_b32_e32 v30, v32
	v_mov_b32_e32 v31, v46
	v_pk_fma_f32 v[22:23], v[94:95], v[30:31], v[22:23] op_sel_hi:[0,1,1]
	v_mov_b32_e32 v46, v33
	v_pk_fma_f32 v[22:23], v[96:97], v[46:47], v[22:23] op_sel_hi:[0,1,1]
	ds_read_b128 v[44:47], v54 offset:32784
	ds_read_b128 v[56:59], v54 offset:36880
	v_pk_add_f32 v[30:31], v[68:69], v[22:23]
	s_waitcnt lgkmcnt(1)
	v_mov_b32_e32 v22, v44
	s_waitcnt lgkmcnt(0)
	v_mov_b32_e32 v23, v56
	v_mov_b32_e32 v56, v45
	v_pk_mul_f32 v[32:33], v[92:93], v[56:57] op_sel_hi:[0,1]
	v_pk_fma_f32 v[22:23], v[90:91], v[22:23], v[32:33] op_sel_hi:[0,1,1]
	v_mov_b32_e32 v32, v46
	v_mov_b32_e32 v33, v58
	v_pk_fma_f32 v[22:23], v[94:95], v[32:33], v[22:23] op_sel_hi:[0,1,1]
	v_mov_b32_e32 v58, v47
	v_pk_fma_f32 v[22:23], v[96:97], v[58:59], v[22:23] op_sel_hi:[0,1,1]
	ds_read_b128 v[44:47], v54 offset:40976
	ds_read_b128 v[56:59], v54 offset:45072
	v_pk_add_f32 v[32:33], v[70:71], v[22:23]
	s_waitcnt lgkmcnt(1)
	v_mov_b32_e32 v22, v44
	s_waitcnt lgkmcnt(0)
	v_mov_b32_e32 v23, v56
	v_mov_b32_e32 v56, v45
	v_pk_mul_f32 v[44:45], v[92:93], v[56:57] op_sel_hi:[0,1]
	v_pk_fma_f32 v[22:23], v[90:91], v[22:23], v[44:45] op_sel_hi:[0,1,1]
	v_mov_b32_e32 v44, v46
	v_mov_b32_e32 v45, v58
	v_pk_fma_f32 v[22:23], v[94:95], v[44:45], v[22:23] op_sel_hi:[0,1,1]
	v_mov_b32_e32 v58, v47
	v_pk_fma_f32 v[22:23], v[96:97], v[58:59], v[22:23] op_sel_hi:[0,1,1]
	ds_read_b128 v[44:47], v54 offset:49168
	ds_read_b128 v[56:59], v54 offset:53264
	v_pk_add_f32 v[22:23], v[72:73], v[22:23]
	s_waitcnt lgkmcnt(1)
	v_mov_b32_e32 v60, v44
	s_waitcnt lgkmcnt(0)
	v_mov_b32_e32 v61, v56
	v_mov_b32_e32 v56, v45
	v_pk_mul_f32 v[44:45], v[92:93], v[56:57] op_sel_hi:[0,1]
	v_pk_fma_f32 v[44:45], v[90:91], v[60:61], v[44:45] op_sel_hi:[0,1,1]
	v_mov_b32_e32 v56, v46
	v_mov_b32_e32 v57, v58
	v_pk_fma_f32 v[44:45], v[94:95], v[56:57], v[44:45] op_sel_hi:[0,1,1]
	v_mov_b32_e32 v58, v47
	v_pk_fma_f32 v[44:45], v[96:97], v[58:59], v[44:45] op_sel_hi:[0,1,1]
	ds_read_b128 v[56:59], v54 offset:57360
	ds_read_b128 v[60:63], v54 offset:61456
	v_pk_add_f32 v[44:45], v[34:35], v[44:45]
	s_waitcnt lgkmcnt(1)
	v_mov_b32_e32 v34, v56
	s_waitcnt lgkmcnt(0)
; #define LAS __attribute__((address_space(3)))
; __device__ NOINL void prep_mod(const LAS Params* lp, LAS unsigned char* lds) {
;     ...
;         for (int k = w * 128; k < w * 128 + 128; k += 4) {
;             const float w0 = wp[(size_t)k * 6144], w1 = wp[(size_t)(k + 1) * 6144], w2 = wp[(size_t)(k + 2) * 6144], w3 = wp[(size_t)(k + 3) * 6144];
; #pragma unroll
;             for (int r = 0; r < 17; ++r) { const f32x4 sv = *(const LAS f32x4*)(sc + r * 1024 + k); acc[r] += sv[0] * w0 + sv[1] * w1 + sv[2] * w2 + sv[3] * w3; }
	v_mov_b32_e32 v35, v60
	v_mov_b32_e32 v60, v57
	v_pk_mul_f32 v[46:47], v[92:93], v[60:61] op_sel_hi:[0,1]
	v_pk_fma_f32 v[34:35], v[90:91], v[34:35], v[46:47] op_sel_hi:[0,1,1]
	v_mov_b32_e32 v46, v58
	v_mov_b32_e32 v47, v62
	v_pk_fma_f32 v[34:35], v[94:95], v[46:47], v[34:35] op_sel_hi:[0,1,1]
	v_mov_b32_e32 v62, v59
	v_pk_fma_f32 v[34:35], v[96:97], v[62:63], v[34:35] op_sel_hi:[0,1,1]
	v_pk_add_f32 v[46:47], v[36:37], v[34:35]
	v_add_u32_e32 v34, 0x10010, v54
	ds_read_b128 v[34:37], v34
	v_mov_b32_e32 v91, v92
	v_mov_b32_e32 v95, v96
	s_waitcnt lgkmcnt(0)
	v_pk_mul_f32 v[34:35], v[90:91], v[34:35]
	s_nop 0
	v_add_f32_e32 v12, v34, v35
	v_pk_mul_f32 v[36:37], v[94:95], v[36:37]
	s_nop 0
	v_add_f32_e32 v12, v36, v12
	v_add_f32_e32 v12, v37, v12
	s_nop 0
	v_add_f32_e32 v60, v43, v12
	v_mov_b32_e32 v38, v6
	s_nop 0
	s_nop 1
	ds_read_b128 v[34:37], v54 offset:4128
	s_waitcnt lgkmcnt(0)
	v_mov_b32_e32 v39, v34
	v_mov_b32_e32 v34, v7
	s_waitcnt vmcnt(6)
	v_pk_mul_f32 v[6:7], v[100:101], v[34:35] op_sel_hi:[0,1]
	v_pk_fma_f32 v[6:7], v[98:99], v[38:39], v[6:7] op_sel_hi:[0,1,1]
	v_mov_b32_e32 v34, v8
	v_mov_b32_e32 v35, v36
	v_mov_b32_e32 v36, v9
	s_waitcnt vmcnt(5)
	v_pk_fma_f32 v[6:7], v[102:103], v[34:35], v[6:7] op_sel_hi:[0,1,1]
	s_waitcnt vmcnt(4)
	v_pk_fma_f32 v[6:7], v[104:105], v[36:37], v[6:7] op_sel_hi:[0,1,1]
	v_pk_add_f32 v[24:25], v[24:25], v[6:7]
	ds_read_b128 v[6:9], v54 offset:8224
	ds_read_b128 v[34:37], v54 offset:12320
	s_waitcnt lgkmcnt(1)
	v_mov_b32_e32 v38, v6
	s_waitcnt lgkmcnt(0)
	v_mov_b32_e32 v39, v34
	v_mov_b32_e32 v34, v7
	v_pk_mul_f32 v[6:7], v[100:101], v[34:35] op_sel_hi:[0,1]
	v_pk_fma_f32 v[6:7], v[98:99], v[38:39], v[6:7] op_sel_hi:[0,1,1]
	v_mov_b32_e32 v34, v8
	v_mov_b32_e32 v35, v36
	v_pk_fma_f32 v[6:7], v[102:103], v[34:35], v[6:7] op_sel_hi:[0,1,1]
	v_mov_b32_e32 v36, v9
	v_pk_fma_f32 v[6:7], v[104:105], v[36:37], v[6:7] op_sel_hi:[0,1,1]
	v_pk_add_f32 v[26:27], v[26:27], v[6:7]
	ds_read_b128 v[6:9], v54 offset:16416
	ds_read_b128 v[34:37], v54 offset:20512
	s_waitcnt lgkmcnt(1)
	v_mov_b32_e32 v38, v6
	s_waitcnt lgkmcnt(0)
	v_mov_b32_e32 v39, v34
	v_mov_b32_e32 v34, v7
	v_pk_mul_f32 v[6:7], v[100:101], v[34:35] op_sel_hi:[0,1]
	v_pk_fma_f32 v[6:7], v[98:99], v[38:39], v[6:7] op_sel_hi:[0,1,1]
	v_mov_b32_e32 v34, v8
	v_mov_b32_e32 v35, v36
	v_pk_fma_f32 v[6:7], v[102:103], v[34:35], v[6:7] op_sel_hi:[0,1,1]
	v_mov_b32_e32 v36, v9
	v_pk_fma_f32 v[6:7], v[104:105], v[36:37], v[6:7] op_sel_hi:[0,1,1]
	v_pk_add_f32 v[28:29], v[28:29], v[6:7]
	ds_read_b128 v[6:9], v54 offset:24608
	ds_read_b128 v[34:37], v54 offset:28704
	s_waitcnt lgkmcnt(1)
	v_mov_b32_e32 v38, v6
	s_waitcnt lgkmcnt(0)
	v_mov_b32_e32 v39, v34
	v_mov_b32_e32 v34, v7
	v_pk_mul_f32 v[6:7], v[100:101], v[34:35] op_sel_hi:[0,1]
	v_pk_fma_f32 v[6:7], v[98:99], v[38:39], v[6:7] op_sel_hi:[0,1,1]
	v_mov_b32_e32 v34, v8
	v_mov_b32_e32 v35, v36
	v_pk_fma_f32 v[6:7], v[102:103], v[34:35], v[6:7] op_sel_hi:[0,1,1]
	v_mov_b32_e32 v36, v9
	v_pk_fma_f32 v[6:7], v[104:105], v[36:37], v[6:7] op_sel_hi:[0,1,1]
	v_pk_add_f32 v[30:31], v[30:31], v[6:7]
	ds_read_b128 v[6:9], v54 offset:32800
	ds_read_b128 v[34:37], v54 offset:36896
	s_waitcnt lgkmcnt(1)
	v_mov_b32_e32 v38, v6
	s_waitcnt lgkmcnt(0)
	v_mov_b32_e32 v39, v34
	v_mov_b32_e32 v34, v7
	v_pk_mul_f32 v[6:7], v[100:101], v[34:35] op_sel_hi:[0,1]
	v_pk_fma_f32 v[6:7], v[98:99], v[38:39], v[6:7] op_sel_hi:[0,1,1]
	v_mov_b32_e32 v34, v8
	v_mov_b32_e32 v35, v36
	v_pk_fma_f32 v[6:7], v[102:103], v[34:35], v[6:7] op_sel_hi:[0,1,1]
	v_mov_b32_e32 v36, v9
	v_pk_fma_f32 v[6:7], v[104:105], v[36:37], v[6:7] op_sel_hi:[0,1,1]
	v_pk_add_f32 v[32:33], v[32:33], v[6:7]
	ds_read_b128 v[6:9], v54 offset:40992
	ds_read_b128 v[34:37], v54 offset:45088
	s_waitcnt lgkmcnt(1)
	v_mov_b32_e32 v38, v6
	s_waitcnt lgkmcnt(0)
	v_mov_b32_e32 v39, v34
	v_mov_b32_e32 v34, v7
	v_pk_mul_f32 v[6:7], v[100:101], v[34:35] op_sel_hi:[0,1]
	v_pk_fma_f32 v[6:7], v[98:99], v[38:39], v[6:7] op_sel_hi:[0,1,1]
	v_mov_b32_e32 v34, v8
	v_mov_b32_e32 v35, v36
	v_pk_fma_f32 v[6:7], v[102:103], v[34:35], v[6:7] op_sel_hi:[0,1,1]
	v_mov_b32_e32 v36, v9
	v_pk_fma_f32 v[6:7], v[104:105], v[36:37], v[6:7] op_sel_hi:[0,1,1]
	v_pk_add_f32 v[34:35], v[22:23], v[6:7]
	ds_read_b128 v[6:9], v54 offset:49184
	ds_read_b128 v[36:39], v54 offset:53280
	s_waitcnt lgkmcnt(1)
	v_mov_b32_e32 v22, v6
	s_waitcnt lgkmcnt(0)
	v_mov_b32_e32 v23, v36
	v_mov_b32_e32 v36, v7
	v_pk_mul_f32 v[6:7], v[100:101], v[36:37] op_sel_hi:[0,1]
	v_pk_fma_f32 v[6:7], v[98:99], v[22:23], v[6:7] op_sel_hi:[0,1,1]
	v_mov_b32_e32 v22, v8
	v_mov_b32_e32 v23, v38
	v_pk_fma_f32 v[6:7], v[102:103], v[22:23], v[6:7] op_sel_hi:[0,1,1]
	v_mov_b32_e32 v38, v9
	v_pk_fma_f32 v[6:7], v[104:105], v[38:39], v[6:7] op_sel_hi:[0,1,1]
	v_pk_add_f32 v[36:37], v[44:45], v[6:7]
	ds_read_b128 v[6:9], v54 offset:57376
	ds_read_b128 v[56:59], v54 offset:61472
	v_mov_b32_e32 v44, v2
	s_waitcnt lgkmcnt(1)
	v_mov_b32_e32 v22, v6
	s_waitcnt lgkmcnt(0)
	v_mov_b32_e32 v23, v56
	v_mov_b32_e32 v56, v7
	v_pk_mul_f32 v[6:7], v[100:101], v[56:57] op_sel_hi:[0,1]
	v_pk_fma_f32 v[6:7], v[98:99], v[22:23], v[6:7] op_sel_hi:[0,1,1]
	v_mov_b32_e32 v22, v8
	v_mov_b32_e32 v23, v58
	v_pk_fma_f32 v[6:7], v[102:103], v[22:23], v[6:7] op_sel_hi:[0,1,1]
	v_mov_b32_e32 v58, v9
	v_pk_fma_f32 v[6:7], v[104:105], v[58:59], v[6:7] op_sel_hi:[0,1,1]
	v_pk_add_f32 v[38:39], v[46:47], v[6:7]
	v_add_u32_e32 v6, 0x10020, v54
	ds_read_b128 v[6:9], v6
	v_mov_b32_e32 v99, v100
	v_mov_b32_e32 v103, v104
	s_waitcnt lgkmcnt(0)
; #define LAS __attribute__((address_space(3)))
; __device__ NOINL void prep_mod(const LAS Params* lp, LAS unsigned char* lds) {
;     ...
;         for (int k = w * 128; k < w * 128 + 128; k += 4) {
;             const float w0 = wp[(size_t)k * 6144], w1 = wp[(size_t)(k + 1) * 6144], w2 = wp[(size_t)(k + 2) * 6144], w3 = wp[(size_t)(k + 3) * 6144];
; #pragma unroll
;             for (int r = 0; r < 17; ++r) { const f32x4 sv = *(const LAS f32x4*)(sc + r * 1024 + k); acc[r] += sv[0] * w0 + sv[1] * w1 + sv[2] * w2 + sv[3] * w3; }
;         }
; #pragma unroll
;         for (int r = 0; r < 17; ++r) red[(w * 17 + r) * 64 + lane] = acc[r];
;         __syncthreads();
;         for (int i = tid; i < 17 * 64; i += 512) {
;             const int r = i >> 6, nn = i & 63; float s = p.mod_b[l * 6144 + n0 + nn];
; #pragma unroll
;             for (int ww = 0; ww < 8; ++ww) s += red[(ww * 17 + r) * 64 + nn];
;             p.modbuf[((size_t)l * 17 + r) * 6144 + n0 + nn] = s;
	v_pk_mul_f32 v[6:7], v[98:99], v[6:7]
	v_pk_mul_f32 v[8:9], v[102:103], v[8:9]
	v_add_f32_e32 v6, v6, v7
	v_add_f32_e32 v6, v8, v6
	v_add_f32_e32 v6, v9, v6
	v_add_f32_e32 v9, v60, v6
	s_nop 1
	s_nop 0
	s_nop 1
	s_nop 0
	ds_read_b128 v[40:43], v54 offset:4144
	v_cmp_ge_i32_e32 vcc, v55, v50
	v_lshl_add_u64 v[20:21], v[20:21], 0, s[16:17]
	s_or_b64 s[20:21], vcc, s[20:21]
	s_waitcnt lgkmcnt(0)
	v_mov_b32_e32 v45, v40
	v_mov_b32_e32 v40, v3
	s_waitcnt vmcnt(2)
	v_pk_mul_f32 v[2:3], v[110:111], v[40:41] op_sel_hi:[0,1]
	v_pk_fma_f32 v[2:3], v[108:109], v[44:45], v[2:3] op_sel_hi:[0,1,1]
	v_mov_b32_e32 v40, v4
	v_mov_b32_e32 v41, v42
	v_mov_b32_e32 v42, v5
	s_waitcnt vmcnt(1)
	v_pk_fma_f32 v[2:3], v[112:113], v[40:41], v[2:3] op_sel_hi:[0,1,1]
	s_waitcnt vmcnt(0)
	v_pk_fma_f32 v[2:3], v[114:115], v[42:43], v[2:3] op_sel_hi:[0,1,1]
	v_pk_add_f32 v[24:25], v[24:25], v[2:3]
	ds_read_b128 v[2:5], v54 offset:8240
	ds_read_b128 v[40:43], v54 offset:12336
	s_waitcnt lgkmcnt(1)
	v_mov_b32_e32 v44, v2
	s_waitcnt lgkmcnt(0)
	v_mov_b32_e32 v45, v40
	v_mov_b32_e32 v40, v3
	v_pk_mul_f32 v[2:3], v[110:111], v[40:41] op_sel_hi:[0,1]
	v_pk_fma_f32 v[2:3], v[108:109], v[44:45], v[2:3] op_sel_hi:[0,1,1]
	v_mov_b32_e32 v40, v4
	v_mov_b32_e32 v41, v42
	v_pk_fma_f32 v[2:3], v[112:113], v[40:41], v[2:3] op_sel_hi:[0,1,1]
	v_mov_b32_e32 v42, v5
	v_pk_fma_f32 v[2:3], v[114:115], v[42:43], v[2:3] op_sel_hi:[0,1,1]
	v_pk_add_f32 v[26:27], v[26:27], v[2:3]
	ds_read_b128 v[2:5], v54 offset:16432
	ds_read_b128 v[40:43], v54 offset:20528
	s_waitcnt lgkmcnt(1)
	v_mov_b32_e32 v44, v2
	s_waitcnt lgkmcnt(0)
	v_mov_b32_e32 v45, v40
	v_mov_b32_e32 v40, v3
	v_pk_mul_f32 v[2:3], v[110:111], v[40:41] op_sel_hi:[0,1]
	v_pk_fma_f32 v[2:3], v[108:109], v[44:45], v[2:3] op_sel_hi:[0,1,1]
	v_mov_b32_e32 v40, v4
	v_mov_b32_e32 v41, v42
	v_pk_fma_f32 v[2:3], v[112:113], v[40:41], v[2:3] op_sel_hi:[0,1,1]
	v_mov_b32_e32 v42, v5
	v_pk_fma_f32 v[2:3], v[114:115], v[42:43], v[2:3] op_sel_hi:[0,1,1]
	v_pk_add_f32 v[28:29], v[28:29], v[2:3]
	ds_read_b128 v[2:5], v54 offset:24624
	ds_read_b128 v[40:43], v54 offset:28720
	s_waitcnt lgkmcnt(1)
	v_mov_b32_e32 v44, v2
	s_waitcnt lgkmcnt(0)
	v_mov_b32_e32 v45, v40
	v_mov_b32_e32 v40, v3
	v_pk_mul_f32 v[2:3], v[110:111], v[40:41] op_sel_hi:[0,1]
	v_pk_fma_f32 v[2:3], v[108:109], v[44:45], v[2:3] op_sel_hi:[0,1,1]
	v_mov_b32_e32 v40, v4
	v_mov_b32_e32 v41, v42
	v_pk_fma_f32 v[2:3], v[112:113], v[40:41], v[2:3] op_sel_hi:[0,1,1]
	v_mov_b32_e32 v42, v5
	v_pk_fma_f32 v[2:3], v[114:115], v[42:43], v[2:3] op_sel_hi:[0,1,1]
	v_pk_add_f32 v[30:31], v[30:31], v[2:3]
	ds_read_b128 v[2:5], v54 offset:32816
	ds_read_b128 v[40:43], v54 offset:36912
	s_waitcnt lgkmcnt(1)
	v_mov_b32_e32 v44, v2
	s_waitcnt lgkmcnt(0)
	v_mov_b32_e32 v45, v40
	v_mov_b32_e32 v40, v3
	v_pk_mul_f32 v[2:3], v[110:111], v[40:41] op_sel_hi:[0,1]
	v_pk_fma_f32 v[2:3], v[108:109], v[44:45], v[2:3] op_sel_hi:[0,1,1]
	v_mov_b32_e32 v40, v4
	v_mov_b32_e32 v41, v42
	v_pk_fma_f32 v[2:3], v[112:113], v[40:41], v[2:3] op_sel_hi:[0,1,1]
	v_mov_b32_e32 v42, v5
	v_pk_fma_f32 v[2:3], v[114:115], v[42:43], v[2:3] op_sel_hi:[0,1,1]
	v_pk_add_f32 v[32:33], v[32:33], v[2:3]
	ds_read_b128 v[2:5], v54 offset:41008
	ds_read_b128 v[40:43], v54 offset:45104
	s_waitcnt lgkmcnt(1)
	v_mov_b32_e32 v44, v2
	s_waitcnt lgkmcnt(0)
	v_mov_b32_e32 v45, v40
	v_mov_b32_e32 v40, v3
	v_pk_mul_f32 v[2:3], v[110:111], v[40:41] op_sel_hi:[0,1]
	v_pk_fma_f32 v[2:3], v[108:109], v[44:45], v[2:3] op_sel_hi:[0,1,1]
	v_mov_b32_e32 v40, v4
	v_mov_b32_e32 v41, v42
	v_pk_fma_f32 v[2:3], v[112:113], v[40:41], v[2:3] op_sel_hi:[0,1,1]
	v_mov_b32_e32 v42, v5
	v_pk_fma_f32 v[2:3], v[114:115], v[42:43], v[2:3] op_sel_hi:[0,1,1]
	v_pk_add_f32 v[34:35], v[34:35], v[2:3]
	ds_read_b128 v[2:5], v54 offset:49200
	ds_read_b128 v[40:43], v54 offset:53296
	s_waitcnt lgkmcnt(1)
	v_mov_b32_e32 v44, v2
	s_waitcnt lgkmcnt(0)
	v_mov_b32_e32 v45, v40
	v_mov_b32_e32 v40, v3
	v_pk_mul_f32 v[2:3], v[110:111], v[40:41] op_sel_hi:[0,1]
	v_pk_fma_f32 v[2:3], v[108:109], v[44:45], v[2:3] op_sel_hi:[0,1,1]
	v_mov_b32_e32 v40, v4
	v_mov_b32_e32 v41, v42
	v_pk_fma_f32 v[2:3], v[112:113], v[40:41], v[2:3] op_sel_hi:[0,1,1]
	v_mov_b32_e32 v42, v5
	v_pk_fma_f32 v[2:3], v[114:115], v[42:43], v[2:3] op_sel_hi:[0,1,1]
	v_pk_add_f32 v[36:37], v[36:37], v[2:3]
	ds_read_b128 v[2:5], v54 offset:57392
	ds_read_b128 v[40:43], v54 offset:61488
	s_waitcnt lgkmcnt(1)
	v_mov_b32_e32 v44, v2
	s_waitcnt lgkmcnt(0)
	v_mov_b32_e32 v45, v40
	v_mov_b32_e32 v40, v3
	v_pk_mul_f32 v[2:3], v[110:111], v[40:41] op_sel_hi:[0,1]
	v_pk_fma_f32 v[2:3], v[108:109], v[44:45], v[2:3] op_sel_hi:[0,1,1]
	v_mov_b32_e32 v40, v4
	v_mov_b32_e32 v41, v42
	v_pk_fma_f32 v[2:3], v[112:113], v[40:41], v[2:3] op_sel_hi:[0,1,1]
	v_mov_b32_e32 v42, v5
	v_pk_fma_f32 v[2:3], v[114:115], v[42:43], v[2:3] op_sel_hi:[0,1,1]
	v_pk_add_f32 v[38:39], v[38:39], v[2:3]
	v_add_u32_e32 v2, 0x10030, v54
	ds_read_b128 v[2:5], v2
	v_mov_b32_e32 v109, v110
	v_mov_b32_e32 v113, v114
	v_add_u32_e32 v54, 64, v54
	s_waitcnt lgkmcnt(0)
	v_pk_mul_f32 v[2:3], v[108:109], v[2:3]
	v_pk_mul_f32 v[4:5], v[112:113], v[4:5]
	v_add_f32_e32 v2, v2, v3
	v_add_f32_e32 v2, v4, v2
	v_add_f32_e32 v2, v5, v2
	v_add_f32_e32 v12, v9, v2
	s_andn2_b64 exec, exec, s[20:21]
	s_cbranch_execnz .LBB0_15
	s_or_b64 exec, exec, s[20:21]
	ds_write2st64_b32 v53, v24, v25 offset1:1
	ds_write2st64_b32 v53, v26, v27 offset0:2 offset1:3
	ds_write2st64_b32 v53, v28, v29 offset0:4 offset1:5
	ds_write2st64_b32 v53, v30, v31 offset0:6 offset1:7
	ds_write2st64_b32 v53, v32, v33 offset0:8 offset1:9
	ds_write2st64_b32 v53, v34, v35 offset0:10 offset1:11
	ds_write2st64_b32 v53, v36, v37 offset0:12 offset1:13
	ds_write2st64_b32 v53, v38, v39 offset0:14 offset1:15
	ds_write_b32 v53, v12 offset:4096
	s_waitcnt lgkmcnt(0)
	s_barrier
	s_and_saveexec_b64 s[20:21], s[8:9]
	s_cbranch_execz .LBB0_8
	s_mul_i32 s4, s22, 0x1800
	s_add_i32 s4, s4, s18
	v_or_b32_e32 v2, s4, v1
	v_ashrrev_i32_e32 v3, 31, v2
	s_mul_hi_i32 s23, s22, 17
	s_mul_i32 s22, s22, 17
	v_lshl_add_u64 v[2:3], v[2:3], 2, s[10:11]
	v_lshl_add_u64 v[4:5], s[18:19], 2, v[14:15]
	s_mov_b64 s[18:19], 0
	v_mov_b32_e32 v6, v10

; __device__ NOINL void prep_filters(const LAS Params* lp, int l, bool with_ctx, LAS unsigned char* lds) {
;     ...
;             for (int j = 0; j < 64; ++j) { const float wv = w3[j * 1024 + col];
; #pragma unroll
;                 for (int pp = 0; pp < 8; ++pp) acc[pp] += h2[pp * 64 + j] * wv; }
.LBB0_128:
	v_add_u32_e32 v120, s16, v22
	v_ashrrev_i32_e32 v121, 31, v120
	v_add_u32_e32 v122, 0x400, v120
	v_add_u32_e32 v124, 0x800, v120
	v_add_u32_e32 v126, 0xc00, v120
	v_lshl_add_u64 v[128:129], v[120:121], 2, s[6:7]
	global_load_dword v120, v[128:129], off
	v_ashrrev_i32_e32 v123, 31, v122
	v_ashrrev_i32_e32 v125, 31, v124
	v_ashrrev_i32_e32 v127, 31, v126
	v_lshl_add_u64 v[128:129], v[122:123], 2, s[6:7]
	v_lshl_add_u64 v[122:123], v[124:125], 2, s[6:7]
	v_lshl_add_u64 v[124:125], v[126:127], 2, s[6:7]
	global_load_dword v126, v[128:129], off
	global_load_dword v128, v[122:123], off
	global_load_dword v122, v[124:125], off
	v_add_u32_e32 v124, s16, v22
	v_add_u32_e32 v130, 0x1000, v124
	v_ashrrev_i32_e32 v131, 31, v130
	v_add_u32_e32 v124, 0x400, v130
	v_add_u32_e32 v132, 0x800, v130
	v_add_u32_e32 v134, 0xc00, v130
	v_lshl_add_u64 v[136:137], v[130:131], 2, s[6:7]
	global_load_dword v130, v[136:137], off
	v_ashrrev_i32_e32 v125, 31, v124
	v_ashrrev_i32_e32 v133, 31, v132
	v_ashrrev_i32_e32 v135, 31, v134
	v_lshl_add_u64 v[136:137], v[124:125], 2, s[6:7]
	v_lshl_add_u64 v[124:125], v[132:133], 2, s[6:7]
	v_lshl_add_u64 v[132:133], v[134:135], 2, s[6:7]
	global_load_dword v134, v[136:137], off
	global_load_dword v136, v[124:125], off
	global_load_dword v124, v[132:133], off
	v_add_u32_e32 v132, s16, v22
	v_add_u32_e32 v138, 0x2000, v132
	v_ashrrev_i32_e32 v139, 31, v138
	v_add_u32_e32 v132, 0x400, v138
	v_add_u32_e32 v140, 0x800, v138
	v_add_u32_e32 v142, 0xc00, v138
	v_lshl_add_u64 v[144:145], v[138:139], 2, s[6:7]
	global_load_dword v138, v[144:145], off
	v_ashrrev_i32_e32 v133, 31, v132
	v_ashrrev_i32_e32 v141, 31, v140
	v_ashrrev_i32_e32 v143, 31, v142
	v_lshl_add_u64 v[144:145], v[132:133], 2, s[6:7]
	v_lshl_add_u64 v[132:133], v[140:141], 2, s[6:7]
	v_lshl_add_u64 v[140:141], v[142:143], 2, s[6:7]
	global_load_dword v142, v[144:145], off
	global_load_dword v144, v[132:133], off
	global_load_dword v132, v[140:141], off
	v_add_u32_e32 v140, s16, v22
	v_add_u32_e32 v146, 0x3000, v140
	v_ashrrev_i32_e32 v147, 31, v146
	v_add_u32_e32 v140, 0x400, v146
	v_add_u32_e32 v148, 0x800, v146
	v_add_u32_e32 v150, 0xc00, v146
	v_lshl_add_u64 v[152:153], v[146:147], 2, s[6:7]
	global_load_dword v146, v[152:153], off
	v_ashrrev_i32_e32 v141, 31, v140
	v_ashrrev_i32_e32 v149, 31, v148
	v_ashrrev_i32_e32 v151, 31, v150
	v_lshl_add_u64 v[152:153], v[140:141], 2, s[6:7]
	v_lshl_add_u64 v[140:141], v[148:149], 2, s[6:7]
	v_lshl_add_u64 v[148:149], v[150:151], 2, s[6:7]
	global_load_dword v150, v[152:153], off
	global_load_dword v152, v[140:141], off
	global_load_dword v140, v[148:149], off
	v_mov_b32_e32 v23, s17
	ds_read_b128 v[46:49], v23
	ds_read_b128 v[50:53], v23 offset:256
	ds_read_b128 v[54:57], v23 offset:512
	ds_read_b128 v[58:61], v23 offset:768
	ds_read_b128 v[62:65], v23 offset:1024
	ds_read_b128 v[66:69], v23 offset:1280
	ds_read_b128 v[70:73], v23 offset:1536
	ds_read_b128 v[74:77], v23 offset:1792
	s_waitcnt lgkmcnt(7)
	v_mov_b32_e32 v86, v46
	s_waitcnt lgkmcnt(6)
	v_mov_b32_e32 v87, v50
	s_waitcnt lgkmcnt(5)
	v_mov_b32_e32 v88, v54
	s_waitcnt lgkmcnt(4)
	v_mov_b32_e32 v89, v58
	s_waitcnt lgkmcnt(3)
	v_mov_b32_e32 v90, v62
	s_waitcnt lgkmcnt(2)
	v_mov_b32_e32 v91, v66
	s_waitcnt lgkmcnt(1)
	v_mov_b32_e32 v92, v70
	s_waitcnt lgkmcnt(0)
	v_mov_b32_e32 v93, v74
	v_mov_b32_e32 v50, v47
	v_mov_b32_e32 v58, v55
	v_mov_b32_e32 v66, v63
	v_mov_b32_e32 v74, v71
	v_mov_b32_e32 v46, v48
	v_mov_b32_e32 v47, v52
	v_mov_b32_e32 v54, v56
	v_mov_b32_e32 v55, v60
	v_mov_b32_e32 v62, v64
	v_mov_b32_e32 v63, v68
	v_mov_b32_e32 v70, v72
	v_mov_b32_e32 v71, v76
	v_mov_b32_e32 v52, v49
	v_mov_b32_e32 v60, v57
	v_mov_b32_e32 v68, v65
	v_mov_b32_e32 v76, v73
	s_waitcnt vmcnt(15)
	v_pk_fma_f32 v[26:27], v[120:121], v[86:87], v[26:27] op_sel_hi:[0,1,1]
	v_pk_fma_f32 v[24:25], v[120:121], v[88:89], v[24:25] op_sel_hi:[0,1,1]
	v_pk_fma_f32 v[20:21], v[120:121], v[90:91], v[20:21] op_sel_hi:[0,1,1]
	v_pk_fma_f32 v[18:19], v[120:121], v[92:93], v[18:19] op_sel_hi:[0,1,1]
	s_waitcnt vmcnt(14)
	v_pk_fma_f32 v[26:27], v[126:127], v[50:51], v[26:27] op_sel_hi:[0,1,1]
	v_pk_fma_f32 v[24:25], v[126:127], v[58:59], v[24:25] op_sel_hi:[0,1,1]
	v_pk_fma_f32 v[20:21], v[126:127], v[66:67], v[20:21] op_sel_hi:[0,1,1]
	v_pk_fma_f32 v[18:19], v[126:127], v[74:75], v[18:19] op_sel_hi:[0,1,1]
	s_waitcnt vmcnt(13)
	v_pk_fma_f32 v[26:27], v[128:129], v[46:47], v[26:27] op_sel_hi:[0,1,1]
	v_pk_fma_f32 v[24:25], v[128:129], v[54:55], v[24:25] op_sel_hi:[0,1,1]
	v_pk_fma_f32 v[20:21], v[128:129], v[62:63], v[20:21] op_sel_hi:[0,1,1]
	v_pk_fma_f32 v[18:19], v[128:129], v[70:71], v[18:19] op_sel_hi:[0,1,1]
	s_waitcnt vmcnt(12)
	v_pk_fma_f32 v[26:27], v[122:123], v[52:53], v[26:27] op_sel_hi:[0,1,1]
	v_pk_fma_f32 v[24:25], v[122:123], v[60:61], v[24:25] op_sel_hi:[0,1,1]
	v_pk_fma_f32 v[20:21], v[122:123], v[68:69], v[20:21] op_sel_hi:[0,1,1]
	v_pk_fma_f32 v[18:19], v[122:123], v[76:77], v[18:19] op_sel_hi:[0,1,1]
	v_mov_b32_e32 v23, s17
	ds_read_b128 v[46:49], v23 offset:16
	ds_read_b128 v[50:53], v23 offset:272
	ds_read_b128 v[54:57], v23 offset:528
	ds_read_b128 v[58:61], v23 offset:784
	ds_read_b128 v[62:65], v23 offset:1040
	ds_read_b128 v[66:69], v23 offset:1296
	ds_read_b128 v[70:73], v23 offset:1552
	ds_read_b128 v[74:77], v23 offset:1808
	s_waitcnt lgkmcnt(7)
	v_mov_b32_e32 v86, v46
	s_waitcnt lgkmcnt(6)
	v_mov_b32_e32 v87, v50
	s_waitcnt lgkmcnt(5)
	v_mov_b32_e32 v88, v54
	s_waitcnt lgkmcnt(4)
	v_mov_b32_e32 v89, v58
	s_waitcnt lgkmcnt(3)
	v_mov_b32_e32 v90, v62
	s_waitcnt lgkmcnt(2)
	v_mov_b32_e32 v91, v66
	s_waitcnt lgkmcnt(1)
	v_mov_b32_e32 v92, v70
	s_waitcnt lgkmcnt(0)
; __device__ __forceinline__ bf16_t f2bf(float f) { return (bf16_t)(pk2(f, f) & 0xFFFFu); }
; __device__ NOINL void prep_filters(const LAS Params* lp, int l, bool with_ctx, LAS unsigned char* lds) {
;     ...
;             for (int j = 0; j < 64; ++j) { const float wv = w3[j * 1024 + col];
; #pragma unroll
;                 for (int pp = 0; pp < 8; ++pp) acc[pp] += h2[pp * 64 + j] * wv; }
;             const int order = col >> 9, side = (col >> 8) & 1, c = col & 255;
;             const float delta = 3.0701134573253945f + (float)c * ((15.350567286626973f - 3.0701134573253945f) / 255.f);
;             bf16_t* Fr = F + ((size_t)order * 256 + c) * (2 * L);
; #pragma unroll
;             for (int pp = 0; pp < 8; ++pp) {
;                 const int pos = p0 + pp; const float tpos = (float)pos / (float)(L - 1);
;                 const float v = acc[pp] * __expf(-tpos * delta);
;                 if (side == 0) Fr[L - pos] = f2bf(v);
;                 else if (pos > 0) Fr[L + pos] = f2bf(v);
;                 else Fr[0] = 0;
;             }
	v_mov_b32_e32 v93, v74
	v_mov_b32_e32 v50, v47
	v_mov_b32_e32 v58, v55
	v_mov_b32_e32 v66, v63
	v_mov_b32_e32 v74, v71
	v_mov_b32_e32 v46, v48
	v_mov_b32_e32 v47, v52
	v_mov_b32_e32 v54, v56
	v_mov_b32_e32 v55, v60
	v_mov_b32_e32 v62, v64
	v_mov_b32_e32 v63, v68
	v_mov_b32_e32 v70, v72
	v_mov_b32_e32 v71, v76
	v_mov_b32_e32 v52, v49
	v_mov_b32_e32 v60, v57
	v_mov_b32_e32 v68, v65
	v_mov_b32_e32 v76, v73
	s_waitcnt vmcnt(11)
	v_pk_fma_f32 v[26:27], v[130:131], v[86:87], v[26:27] op_sel_hi:[0,1,1]
	v_pk_fma_f32 v[24:25], v[130:131], v[88:89], v[24:25] op_sel_hi:[0,1,1]
	v_pk_fma_f32 v[20:21], v[130:131], v[90:91], v[20:21] op_sel_hi:[0,1,1]
	v_pk_fma_f32 v[18:19], v[130:131], v[92:93], v[18:19] op_sel_hi:[0,1,1]
	s_waitcnt vmcnt(10)
	v_pk_fma_f32 v[26:27], v[134:135], v[50:51], v[26:27] op_sel_hi:[0,1,1]
	v_pk_fma_f32 v[24:25], v[134:135], v[58:59], v[24:25] op_sel_hi:[0,1,1]
	v_pk_fma_f32 v[20:21], v[134:135], v[66:67], v[20:21] op_sel_hi:[0,1,1]
	v_pk_fma_f32 v[18:19], v[134:135], v[74:75], v[18:19] op_sel_hi:[0,1,1]
	s_waitcnt vmcnt(9)
	v_pk_fma_f32 v[26:27], v[136:137], v[46:47], v[26:27] op_sel_hi:[0,1,1]
	v_pk_fma_f32 v[24:25], v[136:137], v[54:55], v[24:25] op_sel_hi:[0,1,1]
	v_pk_fma_f32 v[20:21], v[136:137], v[62:63], v[20:21] op_sel_hi:[0,1,1]
	v_pk_fma_f32 v[18:19], v[136:137], v[70:71], v[18:19] op_sel_hi:[0,1,1]
	s_waitcnt vmcnt(8)
	v_pk_fma_f32 v[26:27], v[124:125], v[52:53], v[26:27] op_sel_hi:[0,1,1]
	v_pk_fma_f32 v[24:25], v[124:125], v[60:61], v[24:25] op_sel_hi:[0,1,1]
	v_pk_fma_f32 v[20:21], v[124:125], v[68:69], v[20:21] op_sel_hi:[0,1,1]
	v_pk_fma_f32 v[18:19], v[124:125], v[76:77], v[18:19] op_sel_hi:[0,1,1]
	v_mov_b32_e32 v23, s17
	ds_read_b128 v[46:49], v23 offset:32
	ds_read_b128 v[50:53], v23 offset:288
	ds_read_b128 v[54:57], v23 offset:544
	ds_read_b128 v[58:61], v23 offset:800
	ds_read_b128 v[62:65], v23 offset:1056
	ds_read_b128 v[66:69], v23 offset:1312
	ds_read_b128 v[70:73], v23 offset:1568
	ds_read_b128 v[74:77], v23 offset:1824
	s_waitcnt lgkmcnt(7)
	v_mov_b32_e32 v86, v46
	s_waitcnt lgkmcnt(6)
	v_mov_b32_e32 v87, v50
	s_waitcnt lgkmcnt(5)
	v_mov_b32_e32 v88, v54
	s_waitcnt lgkmcnt(4)
	v_mov_b32_e32 v89, v58
	s_waitcnt lgkmcnt(3)
	v_mov_b32_e32 v90, v62
	s_waitcnt lgkmcnt(2)
	v_mov_b32_e32 v91, v66
	s_waitcnt lgkmcnt(1)
	v_mov_b32_e32 v92, v70
	s_waitcnt lgkmcnt(0)
	v_mov_b32_e32 v93, v74
	v_mov_b32_e32 v50, v47
	v_mov_b32_e32 v58, v55
	v_mov_b32_e32 v66, v63
	v_mov_b32_e32 v74, v71
	v_mov_b32_e32 v46, v48
	v_mov_b32_e32 v47, v52
	v_mov_b32_e32 v54, v56
	v_mov_b32_e32 v55, v60
	v_mov_b32_e32 v62, v64
	v_mov_b32_e32 v63, v68
	v_mov_b32_e32 v70, v72
	v_mov_b32_e32 v71, v76
	v_mov_b32_e32 v52, v49
	v_mov_b32_e32 v60, v57
	v_mov_b32_e32 v68, v65
	v_mov_b32_e32 v76, v73
	s_waitcnt vmcnt(7)
	v_pk_fma_f32 v[26:27], v[138:139], v[86:87], v[26:27] op_sel_hi:[0,1,1]
	v_pk_fma_f32 v[24:25], v[138:139], v[88:89], v[24:25] op_sel_hi:[0,1,1]
	v_pk_fma_f32 v[20:21], v[138:139], v[90:91], v[20:21] op_sel_hi:[0,1,1]
	v_pk_fma_f32 v[18:19], v[138:139], v[92:93], v[18:19] op_sel_hi:[0,1,1]
	s_waitcnt vmcnt(6)
	v_pk_fma_f32 v[26:27], v[142:143], v[50:51], v[26:27] op_sel_hi:[0,1,1]
	v_pk_fma_f32 v[24:25], v[142:143], v[58:59], v[24:25] op_sel_hi:[0,1,1]
	v_pk_fma_f32 v[20:21], v[142:143], v[66:67], v[20:21] op_sel_hi:[0,1,1]
	v_pk_fma_f32 v[18:19], v[142:143], v[74:75], v[18:19] op_sel_hi:[0,1,1]
	s_waitcnt vmcnt(5)
	v_pk_fma_f32 v[26:27], v[144:145], v[46:47], v[26:27] op_sel_hi:[0,1,1]
	v_pk_fma_f32 v[24:25], v[144:145], v[54:55], v[24:25] op_sel_hi:[0,1,1]
	v_pk_fma_f32 v[20:21], v[144:145], v[62:63], v[20:21] op_sel_hi:[0,1,1]
	v_pk_fma_f32 v[18:19], v[144:145], v[70:71], v[18:19] op_sel_hi:[0,1,1]
	s_waitcnt vmcnt(4)
	v_pk_fma_f32 v[26:27], v[132:133], v[52:53], v[26:27] op_sel_hi:[0,1,1]
	v_pk_fma_f32 v[24:25], v[132:133], v[60:61], v[24:25] op_sel_hi:[0,1,1]
	v_pk_fma_f32 v[20:21], v[132:133], v[68:69], v[20:21] op_sel_hi:[0,1,1]
	v_pk_fma_f32 v[18:19], v[132:133], v[76:77], v[18:19] op_sel_hi:[0,1,1]
	v_mov_b32_e32 v23, s17
	ds_read_b128 v[46:49], v23 offset:48
	ds_read_b128 v[50:53], v23 offset:304
	ds_read_b128 v[54:57], v23 offset:560
	ds_read_b128 v[58:61], v23 offset:816
	ds_read_b128 v[62:65], v23 offset:1072
	ds_read_b128 v[66:69], v23 offset:1328
	ds_read_b128 v[70:73], v23 offset:1584
	ds_read_b128 v[74:77], v23 offset:1840
	s_waitcnt lgkmcnt(7)
	v_mov_b32_e32 v86, v46
	s_waitcnt lgkmcnt(6)
	v_mov_b32_e32 v87, v50
	s_waitcnt lgkmcnt(5)
	v_mov_b32_e32 v88, v54
	s_waitcnt lgkmcnt(4)
	v_mov_b32_e32 v89, v58
	s_waitcnt lgkmcnt(3)
	v_mov_b32_e32 v90, v62
	s_waitcnt lgkmcnt(2)
	v_mov_b32_e32 v91, v66
	s_waitcnt lgkmcnt(1)
	v_mov_b32_e32 v92, v70
	s_waitcnt lgkmcnt(0)
	v_mov_b32_e32 v93, v74
	v_mov_b32_e32 v50, v47
	v_mov_b32_e32 v58, v55
	v_mov_b32_e32 v66, v63
	v_mov_b32_e32 v74, v71
	v_mov_b32_e32 v46, v48
	v_mov_b32_e32 v47, v52
	v_mov_b32_e32 v54, v56
	v_mov_b32_e32 v55, v60
	v_mov_b32_e32 v62, v64
	v_mov_b32_e32 v63, v68
	v_mov_b32_e32 v70, v72
	v_mov_b32_e32 v71, v76
	v_mov_b32_e32 v52, v49
	v_mov_b32_e32 v60, v57
	v_mov_b32_e32 v68, v65
	v_mov_b32_e32 v76, v73
	s_waitcnt vmcnt(3)
	v_pk_fma_f32 v[26:27], v[146:147], v[86:87], v[26:27] op_sel_hi:[0,1,1]
	v_pk_fma_f32 v[24:25], v[146:147], v[88:89], v[24:25] op_sel_hi:[0,1,1]
	v_pk_fma_f32 v[20:21], v[146:147], v[90:91], v[20:21] op_sel_hi:[0,1,1]
	v_pk_fma_f32 v[18:19], v[146:147], v[92:93], v[18:19] op_sel_hi:[0,1,1]
	s_waitcnt vmcnt(2)
	v_pk_fma_f32 v[26:27], v[150:151], v[50:51], v[26:27] op_sel_hi:[0,1,1]
	v_pk_fma_f32 v[24:25], v[150:151], v[58:59], v[24:25] op_sel_hi:[0,1,1]
	v_pk_fma_f32 v[20:21], v[150:151], v[66:67], v[20:21] op_sel_hi:[0,1,1]
	v_pk_fma_f32 v[18:19], v[150:151], v[74:75], v[18:19] op_sel_hi:[0,1,1]
	s_waitcnt vmcnt(1)
	v_pk_fma_f32 v[26:27], v[152:153], v[46:47], v[26:27] op_sel_hi:[0,1,1]
	v_pk_fma_f32 v[24:25], v[152:153], v[54:55], v[24:25] op_sel_hi:[0,1,1]
	v_pk_fma_f32 v[20:21], v[152:153], v[62:63], v[20:21] op_sel_hi:[0,1,1]
	v_pk_fma_f32 v[18:19], v[152:153], v[70:71], v[18:19] op_sel_hi:[0,1,1]
	s_waitcnt vmcnt(0)
	v_pk_fma_f32 v[26:27], v[140:141], v[52:53], v[26:27] op_sel_hi:[0,1,1]
	v_pk_fma_f32 v[24:25], v[140:141], v[60:61], v[24:25] op_sel_hi:[0,1,1]
	v_pk_fma_f32 v[20:21], v[140:141], v[68:69], v[20:21] op_sel_hi:[0,1,1]
	v_pk_fma_f32 v[18:19], v[140:141], v[76:77], v[18:19] op_sel_hi:[0,1,1]
	s_add_i32 s17, s17, 64
	s_addk_i32 s16, 0x4000
	s_cmp_eq_u32 s16, 0x10000
	s_cbranch_scc0 .LBB0_128
	v_ashrrev_i32_e32 v22, 9, v22
	v_ashrrev_i32_e32 v23, 31, v22
	v_lshlrev_b64 v[22:23], 8, v[22:23]
	v_or_b32_e32 v22, v22, v12
	v_lshlrev_b64 v[22:23], s64, v[22:23]
	v_lshl_add_u64 v[22:23], v[22:23], 1, s[18:19]
	v_mul_f32_e32 v26, v2, v26
	s_and_saveexec_b64 s[16:17], s[14:15]
	s_xor_b64 s[16:17], exec, s[16:17]
	s_cbranch_execz .LBB0_134
	s_mov_b64 s[38:39], -1
	s_and_b64 vcc, exec, s[20:21]
	s_cbranch_vccz .LBB0_132
	global_store_short v[22:23], v3, off
	s_mov_b64 s[38:39], 0

; __device__ NOINL void prep_filters(const LAS Params* lp, int l, bool with_ctx, LAS unsigned char* lds) {
;     ...
;             for (int j = 0; j < 64; ++j) { const float wv = w3[j * 1024 + col];
; #pragma unroll
;                 for (int pp = 0; pp < 8; ++pp) acc[pp] += h2[pp * 64 + j] * wv; }
.LBB0_433:
	v_add_u32_e32 v166, s1, v24
	v_ashrrev_i32_e32 v167, 31, v166
	v_add_u32_e32 v168, 0x400, v166
	v_add_u32_e32 v170, 0x800, v166
	v_add_u32_e32 v172, 0xc00, v166
	v_lshl_add_u64 v[174:175], v[166:167], 2, s[40:41]
	global_load_dword v166, v[174:175], off
	v_ashrrev_i32_e32 v169, 31, v168
	v_ashrrev_i32_e32 v171, 31, v170
	v_ashrrev_i32_e32 v173, 31, v172
	v_lshl_add_u64 v[174:175], v[168:169], 2, s[40:41]
	v_lshl_add_u64 v[168:169], v[170:171], 2, s[40:41]
	v_lshl_add_u64 v[170:171], v[172:173], 2, s[40:41]
	global_load_dword v172, v[174:175], off
	global_load_dword v174, v[168:169], off
	global_load_dword v168, v[170:171], off
	v_add_u32_e32 v170, s1, v24
	v_add_u32_e32 v176, 0x1000, v170
	v_ashrrev_i32_e32 v177, 31, v176
	v_add_u32_e32 v170, 0x400, v176
	v_add_u32_e32 v178, 0x800, v176
	v_add_u32_e32 v180, 0xc00, v176
	v_lshl_add_u64 v[182:183], v[176:177], 2, s[40:41]
	global_load_dword v176, v[182:183], off
	v_ashrrev_i32_e32 v171, 31, v170
	v_ashrrev_i32_e32 v179, 31, v178
	v_ashrrev_i32_e32 v181, 31, v180
	v_lshl_add_u64 v[182:183], v[170:171], 2, s[40:41]
	v_lshl_add_u64 v[170:171], v[178:179], 2, s[40:41]
	v_lshl_add_u64 v[178:179], v[180:181], 2, s[40:41]
	global_load_dword v180, v[182:183], off
	global_load_dword v182, v[170:171], off
	global_load_dword v170, v[178:179], off
	v_add_u32_e32 v178, s1, v24
	v_add_u32_e32 v186, 0x2000, v178
	v_ashrrev_i32_e32 v187, 31, v186
	v_add_u32_e32 v178, 0x400, v186
	v_add_u32_e32 v188, 0x800, v186
	v_add_u32_e32 v190, 0xc00, v186
	v_lshl_add_u64 v[192:193], v[186:187], 2, s[40:41]
	global_load_dword v186, v[192:193], off
	v_ashrrev_i32_e32 v179, 31, v178
	v_ashrrev_i32_e32 v189, 31, v188
	v_ashrrev_i32_e32 v191, 31, v190
	v_lshl_add_u64 v[192:193], v[178:179], 2, s[40:41]
	v_lshl_add_u64 v[178:179], v[188:189], 2, s[40:41]
	v_lshl_add_u64 v[188:189], v[190:191], 2, s[40:41]
	global_load_dword v190, v[192:193], off
	global_load_dword v192, v[178:179], off
	global_load_dword v178, v[188:189], off
	v_add_u32_e32 v188, s1, v24
	v_add_u32_e32 v194, 0x3000, v188
	v_ashrrev_i32_e32 v195, 31, v194
	v_add_u32_e32 v188, 0x400, v194
	v_add_u32_e32 v196, 0x800, v194
	v_add_u32_e32 v198, 0xc00, v194
	v_lshl_add_u64 v[200:201], v[194:195], 2, s[40:41]
	global_load_dword v194, v[200:201], off
	v_ashrrev_i32_e32 v189, 31, v188
	v_ashrrev_i32_e32 v197, 31, v196
	v_ashrrev_i32_e32 v199, 31, v198
	v_lshl_add_u64 v[200:201], v[188:189], 2, s[40:41]
	v_lshl_add_u64 v[188:189], v[196:197], 2, s[40:41]
	v_lshl_add_u64 v[196:197], v[198:199], 2, s[40:41]
	global_load_dword v198, v[200:201], off
	global_load_dword v200, v[188:189], off
	global_load_dword v188, v[196:197], off
	v_mov_b32_e32 v25, s3
	ds_read_b128 v[44:47], v25
	ds_read_b128 v[48:51], v25 offset:256
	ds_read_b128 v[52:55], v25 offset:512
	ds_read_b128 v[56:59], v25 offset:768
	ds_read_b128 v[60:63], v25 offset:1024
	ds_read_b128 v[64:67], v25 offset:1280
	ds_read_b128 v[68:71], v25 offset:1536
	ds_read_b128 v[72:75], v25 offset:1792
	s_waitcnt lgkmcnt(7)
	v_mov_b32_e32 v84, v44
	s_waitcnt lgkmcnt(6)
	v_mov_b32_e32 v85, v48
	s_waitcnt lgkmcnt(5)
	v_mov_b32_e32 v86, v52
	s_waitcnt lgkmcnt(4)
	v_mov_b32_e32 v87, v56
	s_waitcnt lgkmcnt(3)
	v_mov_b32_e32 v88, v60
	s_waitcnt lgkmcnt(2)
	v_mov_b32_e32 v89, v64
	s_waitcnt lgkmcnt(1)
	v_mov_b32_e32 v90, v68
	s_waitcnt lgkmcnt(0)
	v_mov_b32_e32 v91, v72
	v_mov_b32_e32 v48, v45
	v_mov_b32_e32 v56, v53
	v_mov_b32_e32 v64, v61
	v_mov_b32_e32 v72, v69
	v_mov_b32_e32 v44, v46
	v_mov_b32_e32 v45, v50
	v_mov_b32_e32 v52, v54
	v_mov_b32_e32 v53, v58
	v_mov_b32_e32 v60, v62
	v_mov_b32_e32 v61, v66
	v_mov_b32_e32 v68, v70
	v_mov_b32_e32 v69, v74
	v_mov_b32_e32 v50, v47
	v_mov_b32_e32 v58, v55
	v_mov_b32_e32 v66, v63
	v_mov_b32_e32 v74, v71
	s_waitcnt vmcnt(15)
	v_pk_fma_f32 v[28:29], v[166:167], v[84:85], v[28:29] op_sel_hi:[0,1,1]
	v_pk_fma_f32 v[26:27], v[166:167], v[86:87], v[26:27] op_sel_hi:[0,1,1]
	v_pk_fma_f32 v[22:23], v[166:167], v[88:89], v[22:23] op_sel_hi:[0,1,1]
	v_pk_fma_f32 v[20:21], v[166:167], v[90:91], v[20:21] op_sel_hi:[0,1,1]
	s_waitcnt vmcnt(14)
	v_pk_fma_f32 v[28:29], v[172:173], v[48:49], v[28:29] op_sel_hi:[0,1,1]
	v_pk_fma_f32 v[26:27], v[172:173], v[56:57], v[26:27] op_sel_hi:[0,1,1]
	v_pk_fma_f32 v[22:23], v[172:173], v[64:65], v[22:23] op_sel_hi:[0,1,1]
	v_pk_fma_f32 v[20:21], v[172:173], v[72:73], v[20:21] op_sel_hi:[0,1,1]
	s_waitcnt vmcnt(13)
	v_pk_fma_f32 v[28:29], v[174:175], v[44:45], v[28:29] op_sel_hi:[0,1,1]
	v_pk_fma_f32 v[26:27], v[174:175], v[52:53], v[26:27] op_sel_hi:[0,1,1]
	v_pk_fma_f32 v[22:23], v[174:175], v[60:61], v[22:23] op_sel_hi:[0,1,1]
	v_pk_fma_f32 v[20:21], v[174:175], v[68:69], v[20:21] op_sel_hi:[0,1,1]
	s_waitcnt vmcnt(12)
	v_pk_fma_f32 v[28:29], v[168:169], v[50:51], v[28:29] op_sel_hi:[0,1,1]
	v_pk_fma_f32 v[26:27], v[168:169], v[58:59], v[26:27] op_sel_hi:[0,1,1]
	v_pk_fma_f32 v[22:23], v[168:169], v[66:67], v[22:23] op_sel_hi:[0,1,1]
	v_pk_fma_f32 v[20:21], v[168:169], v[74:75], v[20:21] op_sel_hi:[0,1,1]
	v_mov_b32_e32 v25, s3
	ds_read_b128 v[44:47], v25 offset:16
	ds_read_b128 v[48:51], v25 offset:272
	ds_read_b128 v[52:55], v25 offset:528
	ds_read_b128 v[56:59], v25 offset:784
	ds_read_b128 v[60:63], v25 offset:1040
	ds_read_b128 v[64:67], v25 offset:1296
	ds_read_b128 v[68:71], v25 offset:1552
	ds_read_b128 v[72:75], v25 offset:1808
	s_waitcnt lgkmcnt(7)
	v_mov_b32_e32 v84, v44
	s_waitcnt lgkmcnt(6)
	v_mov_b32_e32 v85, v48
	s_waitcnt lgkmcnt(5)
	v_mov_b32_e32 v86, v52
	s_waitcnt lgkmcnt(4)
	v_mov_b32_e32 v87, v56
	s_waitcnt lgkmcnt(3)
	v_mov_b32_e32 v88, v60
	s_waitcnt lgkmcnt(2)
	v_mov_b32_e32 v89, v64
	s_waitcnt lgkmcnt(1)
; __device__ __forceinline__ bf16_t f2bf(float f) { return (bf16_t)(pk2(f, f) & 0xFFFFu); }
; __device__ NOINL void prep_filters(const LAS Params* lp, int l, bool with_ctx, LAS unsigned char* lds) {
;     ...
;             for (int j = 0; j < 64; ++j) { const float wv = w3[j * 1024 + col];
; #pragma unroll
;                 for (int pp = 0; pp < 8; ++pp) acc[pp] += h2[pp * 64 + j] * wv; }
;             const int order = col >> 9, side = (col >> 8) & 1, c = col & 255;
;             const float delta = 3.0701134573253945f + (float)c * ((15.350567286626973f - 3.0701134573253945f) / 255.f);
;             bf16_t* Fr = F + ((size_t)order * 256 + c) * (2 * L);
; #pragma unroll
;             for (int pp = 0; pp < 8; ++pp) {
;                 const int pos = p0 + pp; const float tpos = (float)pos / (float)(L - 1);
;                 const float v = acc[pp] * __expf(-tpos * delta);
;                 if (side == 0) Fr[L - pos] = f2bf(v);
;                 else if (pos > 0) Fr[L + pos] = f2bf(v);
;                 else Fr[0] = 0;
;             }
	v_mov_b32_e32 v90, v68
	s_waitcnt lgkmcnt(0)
	v_mov_b32_e32 v91, v72
	v_mov_b32_e32 v48, v45
	v_mov_b32_e32 v56, v53
	v_mov_b32_e32 v64, v61
	v_mov_b32_e32 v72, v69
	v_mov_b32_e32 v44, v46
	v_mov_b32_e32 v45, v50
	v_mov_b32_e32 v52, v54
	v_mov_b32_e32 v53, v58
	v_mov_b32_e32 v60, v62
	v_mov_b32_e32 v61, v66
	v_mov_b32_e32 v68, v70
	v_mov_b32_e32 v69, v74
	v_mov_b32_e32 v50, v47
	v_mov_b32_e32 v58, v55
	v_mov_b32_e32 v66, v63
	v_mov_b32_e32 v74, v71
	s_waitcnt vmcnt(11)
	v_pk_fma_f32 v[28:29], v[176:177], v[84:85], v[28:29] op_sel_hi:[0,1,1]
	v_pk_fma_f32 v[26:27], v[176:177], v[86:87], v[26:27] op_sel_hi:[0,1,1]
	v_pk_fma_f32 v[22:23], v[176:177], v[88:89], v[22:23] op_sel_hi:[0,1,1]
	v_pk_fma_f32 v[20:21], v[176:177], v[90:91], v[20:21] op_sel_hi:[0,1,1]
	s_waitcnt vmcnt(10)
	v_pk_fma_f32 v[28:29], v[180:181], v[48:49], v[28:29] op_sel_hi:[0,1,1]
	v_pk_fma_f32 v[26:27], v[180:181], v[56:57], v[26:27] op_sel_hi:[0,1,1]
	v_pk_fma_f32 v[22:23], v[180:181], v[64:65], v[22:23] op_sel_hi:[0,1,1]
	v_pk_fma_f32 v[20:21], v[180:181], v[72:73], v[20:21] op_sel_hi:[0,1,1]
	s_waitcnt vmcnt(9)
	v_pk_fma_f32 v[28:29], v[182:183], v[44:45], v[28:29] op_sel_hi:[0,1,1]
	v_pk_fma_f32 v[26:27], v[182:183], v[52:53], v[26:27] op_sel_hi:[0,1,1]
	v_pk_fma_f32 v[22:23], v[182:183], v[60:61], v[22:23] op_sel_hi:[0,1,1]
	v_pk_fma_f32 v[20:21], v[182:183], v[68:69], v[20:21] op_sel_hi:[0,1,1]
	s_waitcnt vmcnt(8)
	v_pk_fma_f32 v[28:29], v[170:171], v[50:51], v[28:29] op_sel_hi:[0,1,1]
	v_pk_fma_f32 v[26:27], v[170:171], v[58:59], v[26:27] op_sel_hi:[0,1,1]
	v_pk_fma_f32 v[22:23], v[170:171], v[66:67], v[22:23] op_sel_hi:[0,1,1]
	v_pk_fma_f32 v[20:21], v[170:171], v[74:75], v[20:21] op_sel_hi:[0,1,1]
	v_mov_b32_e32 v25, s3
	ds_read_b128 v[44:47], v25 offset:32
	ds_read_b128 v[48:51], v25 offset:288
	ds_read_b128 v[52:55], v25 offset:544
	ds_read_b128 v[56:59], v25 offset:800
	ds_read_b128 v[60:63], v25 offset:1056
	ds_read_b128 v[64:67], v25 offset:1312
	ds_read_b128 v[68:71], v25 offset:1568
	ds_read_b128 v[72:75], v25 offset:1824
	s_waitcnt lgkmcnt(7)
	v_mov_b32_e32 v84, v44
	s_waitcnt lgkmcnt(6)
	v_mov_b32_e32 v85, v48
	s_waitcnt lgkmcnt(5)
	v_mov_b32_e32 v86, v52
	s_waitcnt lgkmcnt(4)
	v_mov_b32_e32 v87, v56
	s_waitcnt lgkmcnt(3)
	v_mov_b32_e32 v88, v60
	s_waitcnt lgkmcnt(2)
	v_mov_b32_e32 v89, v64
	s_waitcnt lgkmcnt(1)
	v_mov_b32_e32 v90, v68
	s_waitcnt lgkmcnt(0)
	v_mov_b32_e32 v91, v72
	v_mov_b32_e32 v48, v45
	v_mov_b32_e32 v56, v53
	v_mov_b32_e32 v64, v61
	v_mov_b32_e32 v72, v69
	v_mov_b32_e32 v44, v46
	v_mov_b32_e32 v45, v50
	v_mov_b32_e32 v52, v54
	v_mov_b32_e32 v53, v58
	v_mov_b32_e32 v60, v62
	v_mov_b32_e32 v61, v66
	v_mov_b32_e32 v68, v70
	v_mov_b32_e32 v69, v74
	v_mov_b32_e32 v50, v47
	v_mov_b32_e32 v58, v55
	v_mov_b32_e32 v66, v63
	v_mov_b32_e32 v74, v71
	s_waitcnt vmcnt(7)
	v_pk_fma_f32 v[28:29], v[186:187], v[84:85], v[28:29] op_sel_hi:[0,1,1]
	v_pk_fma_f32 v[26:27], v[186:187], v[86:87], v[26:27] op_sel_hi:[0,1,1]
	v_pk_fma_f32 v[22:23], v[186:187], v[88:89], v[22:23] op_sel_hi:[0,1,1]
	v_pk_fma_f32 v[20:21], v[186:187], v[90:91], v[20:21] op_sel_hi:[0,1,1]
	s_waitcnt vmcnt(6)
	v_pk_fma_f32 v[28:29], v[190:191], v[48:49], v[28:29] op_sel_hi:[0,1,1]
	v_pk_fma_f32 v[26:27], v[190:191], v[56:57], v[26:27] op_sel_hi:[0,1,1]
	v_pk_fma_f32 v[22:23], v[190:191], v[64:65], v[22:23] op_sel_hi:[0,1,1]
	v_pk_fma_f32 v[20:21], v[190:191], v[72:73], v[20:21] op_sel_hi:[0,1,1]
	s_waitcnt vmcnt(5)
	v_pk_fma_f32 v[28:29], v[192:193], v[44:45], v[28:29] op_sel_hi:[0,1,1]
	v_pk_fma_f32 v[26:27], v[192:193], v[52:53], v[26:27] op_sel_hi:[0,1,1]
	v_pk_fma_f32 v[22:23], v[192:193], v[60:61], v[22:23] op_sel_hi:[0,1,1]
	v_pk_fma_f32 v[20:21], v[192:193], v[68:69], v[20:21] op_sel_hi:[0,1,1]
	s_waitcnt vmcnt(4)
	v_pk_fma_f32 v[28:29], v[178:179], v[50:51], v[28:29] op_sel_hi:[0,1,1]
	v_pk_fma_f32 v[26:27], v[178:179], v[58:59], v[26:27] op_sel_hi:[0,1,1]
	v_pk_fma_f32 v[22:23], v[178:179], v[66:67], v[22:23] op_sel_hi:[0,1,1]
	v_pk_fma_f32 v[20:21], v[178:179], v[74:75], v[20:21] op_sel_hi:[0,1,1]
	v_mov_b32_e32 v25, s3
	ds_read_b128 v[44:47], v25 offset:48
	ds_read_b128 v[48:51], v25 offset:304
	ds_read_b128 v[52:55], v25 offset:560
	ds_read_b128 v[56:59], v25 offset:816
	ds_read_b128 v[60:63], v25 offset:1072
	ds_read_b128 v[64:67], v25 offset:1328
	ds_read_b128 v[68:71], v25 offset:1584
	ds_read_b128 v[72:75], v25 offset:1840
	s_waitcnt lgkmcnt(7)
	v_mov_b32_e32 v84, v44
	s_waitcnt lgkmcnt(6)
	v_mov_b32_e32 v85, v48
	s_waitcnt lgkmcnt(5)
	v_mov_b32_e32 v86, v52
	s_waitcnt lgkmcnt(4)
	v_mov_b32_e32 v87, v56
	s_waitcnt lgkmcnt(3)
	v_mov_b32_e32 v88, v60
	s_waitcnt lgkmcnt(2)
	v_mov_b32_e32 v89, v64
	s_waitcnt lgkmcnt(1)
	v_mov_b32_e32 v90, v68
	s_waitcnt lgkmcnt(0)
	v_mov_b32_e32 v91, v72
	v_mov_b32_e32 v48, v45
	v_mov_b32_e32 v56, v53
	v_mov_b32_e32 v64, v61
	v_mov_b32_e32 v72, v69
	v_mov_b32_e32 v44, v46
	v_mov_b32_e32 v45, v50
	v_mov_b32_e32 v52, v54
	v_mov_b32_e32 v53, v58
	v_mov_b32_e32 v60, v62
	v_mov_b32_e32 v61, v66
	v_mov_b32_e32 v68, v70
	v_mov_b32_e32 v69, v74
	v_mov_b32_e32 v50, v47
	v_mov_b32_e32 v58, v55
	v_mov_b32_e32 v66, v63
	v_mov_b32_e32 v74, v71
	s_waitcnt vmcnt(3)
	v_pk_fma_f32 v[28:29], v[194:195], v[84:85], v[28:29] op_sel_hi:[0,1,1]
	v_pk_fma_f32 v[26:27], v[194:195], v[86:87], v[26:27] op_sel_hi:[0,1,1]
	v_pk_fma_f32 v[22:23], v[194:195], v[88:89], v[22:23] op_sel_hi:[0,1,1]
	v_pk_fma_f32 v[20:21], v[194:195], v[90:91], v[20:21] op_sel_hi:[0,1,1]
	s_waitcnt vmcnt(2)
	v_pk_fma_f32 v[28:29], v[198:199], v[48:49], v[28:29] op_sel_hi:[0,1,1]
	v_pk_fma_f32 v[26:27], v[198:199], v[56:57], v[26:27] op_sel_hi:[0,1,1]
	v_pk_fma_f32 v[22:23], v[198:199], v[64:65], v[22:23] op_sel_hi:[0,1,1]
	v_pk_fma_f32 v[20:21], v[198:199], v[72:73], v[20:21] op_sel_hi:[0,1,1]
	s_waitcnt vmcnt(1)
	v_pk_fma_f32 v[28:29], v[200:201], v[44:45], v[28:29] op_sel_hi:[0,1,1]
	v_pk_fma_f32 v[26:27], v[200:201], v[52:53], v[26:27] op_sel_hi:[0,1,1]
	v_pk_fma_f32 v[22:23], v[200:201], v[60:61], v[22:23] op_sel_hi:[0,1,1]
	v_pk_fma_f32 v[20:21], v[200:201], v[68:69], v[20:21] op_sel_hi:[0,1,1]
	s_waitcnt vmcnt(0)
	v_pk_fma_f32 v[28:29], v[188:189], v[50:51], v[28:29] op_sel_hi:[0,1,1]
	v_pk_fma_f32 v[26:27], v[188:189], v[58:59], v[26:27] op_sel_hi:[0,1,1]
	v_pk_fma_f32 v[22:23], v[188:189], v[66:67], v[22:23] op_sel_hi:[0,1,1]
	v_pk_fma_f32 v[20:21], v[188:189], v[74:75], v[20:21] op_sel_hi:[0,1,1]
	s_add_i32 s3, s3, 64
	s_addk_i32 s1, 0x4000
	s_cmp_eq_u32 s1, 0x10000
	s_cbranch_scc0 .LBB0_433
	v_ashrrev_i32_e32 v24, 9, v24
	v_ashrrev_i32_e32 v25, 31, v24
	v_lshlrev_b64 v[24:25], 21, v[24:25]
	v_lshl_add_u64 v[24:25], v[14:15], 0, v[24:25]
	v_mul_f32_e32 v28, v0, v28
	s_and_saveexec_b64 s[4:5], s[50:51]
	s_xor_b64 s[52:53], exec, s[4:5]
	s_cbranch_execz .LBB0_439
	s_mov_b64 s[90:91], -1
	s_and_b64 vcc, exec, s[54:55]
	s_cbranch_vccz .LBB0_437
	global_store_short v[24:25], v1, off
	s_mov_b64 s[90:91], 0
